# E32: loop-edge edit (back-edge rotation 7.11) on both attention inner loops, on top of E28
# baseline (speedup 1.0000x reference)
; __device__ __forceinline__ unsigned cvtb(float lo, float hi) { const f32x2 v = {lo, hi}; const bf16x2v_t r = __builtin_convertvector(v, bf16x2v_t); return __builtin_bit_cast(unsigned, r); }
; __device__ __forceinline__ int v_st(int k, int c) { const int kk = k; return ((kk >> 3) * 4 + (c >> 5)) * 512 + ((kk & 7) * 32 + (c & 31)) * 2; }
; __device__ __forceinline__ int v_rd_base(int lane) { return ((lane & 3) << 3) | (((lane >> 2) & 3) << 6) | (((lane >> 4) & 1) << 5) | (((lane >> 5) & 1) << 8); }
; template <int NQK, int SD, bool MI> ...
;     ...
;   if constexpr (MI) {
; #pragma unroll
;     for (int d0 = 0; d0 < NQK; ++d0) { u32x4 w = *reinterpret_cast<u32x4*>(&qr[d0]);
; #pragma unroll
;       for (int e = 0; e < 4; ++e) { const float lo = __uint_as_float(w[e] << 16) * C, hi2 = __uint_as_float(w[e] & 0xffff0000u) * C; w[e] = cvtb(lo, hi2); }
;       qr[d0] = *reinterpret_cast<bf16x8*>(&w); }
;   }
;   constexpr bool RECOMP = false;
;   const int p_voffV = ((tid >> 4) * ldv + (tid & 15) * 8) * 2, p_vstV = v_st(tid >> 4, (tid & 15) * 8);
;   const int p_voffK = ((tid >> 3) * ldk + (tid & 7) * 8) * 2, p_ldsK = (tid >> 3) * KROW + (tid & 7) * 16;
;     ...
;   const auto rK = __builtin_amdgcn_make_buffer_rsrc((void*)Kh, 0, 0x7ffffff0, 0x00020000);
;   const auto rV = __builtin_amdgcn_make_buffer_rsrc((void*)Vh, 0, 0x7ffffff0, 0x00020000);
;   const int vb0 = (int)(uintptr_t)V_lds + v_rd_base(lane);
;   struct { u32x4 vs0, vs1; u32x4 ks[NP]; } sr_[SD];
;     ...
;   f32x16 pA0, pA1, pB0, pB1; float mnA, mnB, alA, alB; bf16x8 pa0, pa1, pa2, pa3; const int NT = seq / 64;
;   constexpr int SE = 0, SO = SD - 1;
;   if (__builtin_amdgcn_readfirstlane(tid) >= 256) __builtin_amdgcn_s_setprio(1);
;   __syncthreads();
;     ...
;   SLOAD(SE, 0); asm volatile("s_waitcnt vmcnt(0)" ::: "memory"); SWRITE(0, SE); __syncthreads();
;   if constexpr (MI) { qkt_mi<NQK>(pA0, pA1, K_lds, qr, r32, hi, minit); decide_mi(pA0, pA1, minit, Mref, alA, thr2, true);
; #pragma unroll
;     for (int r = 0; r < 16; ++r) pA0[r] = __builtin_amdgcn_exp2f(pA0[r]); }
;   else { qkt<NQK>(pA0, pA1, K_lds, qr, r32, hi); partialSM(pA0, pA1, m_reg, mnA, alA, C, thr); }
;   SLOAD(SO, 64); if constexpr (SD == 2) { if (2 < NT) SLOAD(SE, 2 * 64); }
.LBB0_1285:
	s_lshl_b32 s7, s6, 1
	s_add_u32 s36, s25, s7
	s_addc_u32 s7, s44, 0
	s_and_b32 s6, s6, 0x180
	v_ashrrev_i32_e32 v32, 4, v16
	v_lshlrev_b32_e32 v33, 3, v16
	s_lshl_b32 s6, s6, 1
	v_and_b32_e32 v18, 0x78, v33
	v_lshlrev_b32_e32 v19, 10, v32
	s_add_u32 s28, s90, s6
	v_lshl_or_b32 v216, v18, 1, v19
	v_lshlrev_b32_e32 v18, 4, v16
	s_addc_u32 s6, s91, 0
	v_ashrrev_i32_e32 v34, 3, v16
	v_and_b32_e32 v35, 0x70, v18
	v_lshl_or_b32 v217, v34, 11, v35
	s_and_b32 s37, s7, 0xffff
	s_mov_b32 s38, s30
	s_and_b32 s29, s6, 0xffff
	s_mov_b32 s39, s31
	s_waitcnt vmcnt(63) expcnt(7) lgkmcnt(15)
	s_barrier
	buffer_load_dwordx4 v[18:21], v216, s[28:31], 0 offen
	buffer_load_dwordx4 v[22:25], v216, s[28:31], s74 offen
	buffer_load_dwordx4 v[26:29], v217, s[36:39], 0 offen
	s_waitcnt vmcnt(6)
	v_lshlrev_b32_e32 v30, 16, v12
	v_and_b32_e32 v31, 0xffff0000, v12
	s_mov_b32 s8, 0x3e38aa3b
	v_lshlrev_b32_e32 v12, 16, v13
	v_and_b32_e32 v13, 0xffff0000, v13
	v_pk_mul_f32 v[12:13], v[12:13], s[8:9] op_sel_hi:[1,0]
	v_and_b32_e32 v200, 0xffffffe0, v17
	v_cvt_pk_bf16_f32 v147, v12, v13
	v_lshlrev_b32_e32 v12, 16, v14
	v_and_b32_e32 v13, 0xffff0000, v14
	v_pk_mul_f32 v[12:13], v[12:13], s[8:9] op_sel_hi:[1,0]
	v_and_b32_e32 v17, 0x3fffffc0, v16
	v_cvt_pk_bf16_f32 v148, v12, v13
	v_lshlrev_b32_e32 v12, 16, v15
	v_and_b32_e32 v13, 0xffff0000, v15
	v_pk_mul_f32 v[12:13], v[12:13], s[8:9] op_sel_hi:[1,0]
	s_add_i32 s6, 16, 0x12c00
	v_cvt_pk_bf16_f32 v149, v12, v13
	s_waitcnt vmcnt(5)
	v_lshlrev_b32_e32 v12, 16, v8
	v_and_b32_e32 v13, 0xffff0000, v8
	v_lshlrev_b32_e32 v8, 16, v9
	v_and_b32_e32 v9, 0xffff0000, v9
	v_pk_mul_f32 v[8:9], v[8:9], s[8:9] op_sel_hi:[1,0]
	v_and_b32_e32 v189, 31, v16
	v_cvt_pk_bf16_f32 v151, v8, v9
	v_lshlrev_b32_e32 v8, 16, v10
	v_and_b32_e32 v9, 0xffff0000, v10
	v_pk_mul_f32 v[8:9], v[8:9], s[8:9] op_sel_hi:[1,0]
	v_lshl_add_u32 v191, v17, 2, s6
	v_cvt_pk_bf16_f32 v152, v8, v9
	v_lshlrev_b32_e32 v8, 16, v11
	v_and_b32_e32 v9, 0xffff0000, v11
	v_pk_mul_f32 v[8:9], v[8:9], s[8:9] op_sel_hi:[1,0]
	s_movk_i32 s6, 0x90
	v_cvt_pk_bf16_f32 v153, v8, v9
	s_waitcnt vmcnt(4)
	v_lshlrev_b32_e32 v8, 16, v4
	v_and_b32_e32 v9, 0xffff0000, v4
	v_lshlrev_b32_e32 v4, 16, v5
	v_and_b32_e32 v5, 0xffff0000, v5
	v_pk_mul_f32 v[4:5], v[4:5], s[8:9] op_sel_hi:[1,0]
	v_pk_mul_f32 v[8:9], v[8:9], s[8:9] op_sel_hi:[1,0]
	v_cvt_pk_bf16_f32 v155, v4, v5
	v_lshlrev_b32_e32 v4, 16, v6
	v_and_b32_e32 v5, 0xffff0000, v6
	v_pk_mul_f32 v[4:5], v[4:5], s[8:9] op_sel_hi:[1,0]
	v_bfe_u32 v6, v33, 5, 2
	v_cvt_pk_bf16_f32 v156, v4, v5
	v_lshrrev_b32_e32 v5, 5, v16
	v_cvt_pk_bf16_f32 v154, v8, v9
	v_and_or_b32 v5, v5, s40, v6
	v_lshlrev_b32_e32 v6, 5, v32
	v_and_b32_e32 v8, 24, v33
	v_and_or_b32 v6, v6, s41, v8
	v_lshlrev_b32_e32 v6, 1, v6
	v_lshl_or_b32 v5, v5, 9, v6
	v_lshlrev_b32_e32 v4, 16, v7
	v_add_u32_e32 v218, 16, v5
	v_and_b32_e32 v5, 0xffff0000, v7
	v_mul_lo_u32 v6, v34, s6
	v_mul_u32_u24_e32 v220, 0x90, v189
	v_pk_mul_f32 v[4:5], v[4:5], s[8:9] op_sel_hi:[1,0]
	v_pk_mul_f32 v[12:13], v[12:13], s[8:9] op_sel_hi:[1,0]
	v_add3_u32 v219, v6, v35, 16
	v_add3_u32 v221, 16, v220, v198
	v_cvt_pk_bf16_f32 v157, v4, v5
	s_waitcnt vmcnt(3)
	v_lshlrev_b32_e32 v4, 16, v0
	v_and_b32_e32 v5, 0xffff0000, v0
	s_mov_b32 s6, 0x18000
	v_cvt_pk_bf16_f32 v150, v12, v13
	s_waitcnt vmcnt(0)
	s_waitcnt vmcnt(2)
	ds_write_b128 v218, v[18:21]
	s_waitcnt vmcnt(1)
	ds_write_b128 v218, v[22:25] offset:8192
	s_waitcnt vmcnt(0)
	ds_write_b128 v219, v[26:29] offset:49152
	s_waitcnt lgkmcnt(0)
	s_barrier
	ds_read_b128 v[8:11], v221 offset:49152
	v_pk_mul_f32 v[32:33], v[4:5], s[8:9] op_sel_hi:[1,0]
	ds_read_b128 v[4:7], v221 offset:53760
	ds_read_b128 v[12:15], v221 offset:49184
	buffer_load_dwordx4 v[48:51], v216, s[28:31], s75 offen
	buffer_load_dwordx4 v[52:55], v216, s[28:31], s6 offen
	buffer_load_dwordx4 v[56:59], v217, s[36:39], s31 offen
	v_pk_mul_f32 v[30:31], v[30:31], s[8:9] op_sel_hi:[1,0]
	v_lshlrev_b32_e32 v0, 16, v1
	v_cvt_pk_bf16_f32 v146, v30, v31
	v_and_b32_e32 v1, 0xffff0000, v1
	v_and_b32_e32 v64, 63, v16
	s_waitcnt lgkmcnt(2)
	v_mfma_f32_32x32x16_bf16 v[16:31], v[8:11], v[146:149], 0
	v_mul_f32_e64 v0, v0, s8
	v_mul_f32_e64 v1, v1, s8
	ds_read_b128 v[8:11], v221 offset:53792
	v_cvt_pk_bf16_f32 v159, v0, v1
	v_lshlrev_b32_e32 v0, 16, v2
	v_and_b32_e32 v1, 0xffff0000, v2
	v_cvt_pk_bf16_f32 v158, v32, v33
	v_pk_mul_f32 v[0:1], v[0:1], s[8:9] op_sel_hi:[1,0]
	s_waitcnt lgkmcnt(2)
	v_mfma_f32_32x32x16_bf16 v[32:47], v[4:7], v[146:149], 0
	v_cvt_pk_bf16_f32 v160, v0, v1
	v_lshlrev_b32_e32 v0, 16, v3
	v_and_b32_e32 v1, 0xffff0000, v3
	v_mul_f32_e64 v0, v0, s8
	v_mul_f32_e64 v1, v1, s8
	v_lshlrev_b32_e32 v4, 3, v64
	v_cvt_pk_bf16_f32 v161, v0, v1
	v_lshlrev_b32_e32 v0, 4, v64
	v_and_b32_e32 v5, 0xc0, v0
	v_lshlrev_b32_e32 v6, 1, v64
	v_and_or_b32 v5, v4, 24, v5
	v_and_b32_e32 v6, 32, v6
	v_and_b32_e32 v4, 0x100, v4
	s_cmp_lg_u32 16, -1
	s_waitcnt lgkmcnt(1)
	v_mfma_f32_32x32x16_bf16 v[16:31], v[12:15], v[150:153], v[16:31]
	v_or3_b32 v12, v5, v6, v4
	s_cselect_b32 s6, 16, 0
	v_add_u32_e32 v214, s6, v12
	s_mov_b32 s6, 0x28000
	ds_read_b128 v[0:3], v221 offset:49216
	s_mov_b32 s8, 0
	s_mov_b32 s9, s8
	s_waitcnt lgkmcnt(1)
	v_mfma_f32_32x32x16_bf16 v[32:47], v[8:11], v[150:153], v[32:47]
	ds_read_b128 v[4:7], v221 offset:53824
	ds_read_b128 v[8:11], v221 offset:49248
	ds_read_b128 v[60:63], v221 offset:53856
	buffer_load_dwordx4 v[162:165], v216, s[28:31], s31 offen
	buffer_load_dwordx4 v[166:169], v216, s[28:31], s6 offen
	buffer_load_dwordx4 v[170:173], v217, s[36:39], s76 offen
	s_waitcnt vmcnt(3)
	s_mov_b32 s10, s8
	s_mov_b32 s11, s8
	s_waitcnt lgkmcnt(3)
; #define SWRITE(b, i) do { STG_T() const int _sv = VSTV(), _sk = LDSK(); *(u32x4*)(V_lds + (b) * SHM_V + _sv) = sr_[i].vs0; *(u32x4*)(V_lds + (b) * SHM_V + _sv + 8192) = sr_[i].vs1; \
;     _Pragma("unroll") for (int _p = 0; _p < NP; ++_p) *(u32x4*)(K_lds + (b) * KT + _sk + _p * 128) = sr_[i].ks[_p]; } while (0)
; #define SWAIT() do { if constexpr (SD == 2) { if constexpr (NP == 1) asm volatile("s_waitcnt vmcnt(3)" ::: "memory"); else asm volatile("s_waitcnt vmcnt(5)" ::: "memory"); } else asm volatile("s_waitcnt vmcnt(0)" ::: "memory"); } while (0)
; __device__ __forceinline__ void decide_mi(f32x16& p0, f32x16& p1, f32x16& minit, float& M, float& alpha, const float thr2, const bool first) {
;   float pmax = p0[0];
; #pragma unroll
;   for (int r = 1; r < 16; ++r) pmax = fmaxf(pmax, p0[r]);
; #pragma unroll
;   for (int r = 0; r < 16; ++r) pmax = fmaxf(pmax, p1[r]);
;   { auto rr = __builtin_amdgcn_permlane32_swap(__float_as_uint(pmax), __float_as_uint(pmax), false, false);
;     pmax = fmaxf(__uint_as_float(rr[0]), __uint_as_float(rr[1])); }
;   if (__builtin_expect(!first && __all(pmax <= thr2), 1)) { alpha = 1.f; }
;   else { const float delta = first ? pmax : fmaxf(pmax, 0.f); alpha = first ? 1.f : __builtin_amdgcn_exp2f(-delta); M += delta;
; #pragma unroll
;     for (int r = 0; r < 16; ++r) { p0[r] -= delta; p1[r] -= delta; minit[r] = -M; } }
; }
; template <int NQK, int SD, bool MI> ...
;     ...
;   if constexpr (MI) { qkt_mi<NQK>(pA0, pA1, K_lds, qr, r32, hi, minit); decide_mi(pA0, pA1, minit, Mref, alA, thr2, true);
; #pragma unroll
;     for (int r = 0; r < 16; ++r) pA0[r] = __builtin_amdgcn_exp2f(pA0[r]); }
;   else { qkt<NQK>(pA0, pA1, K_lds, qr, r32, hi); partialSM(pA0, pA1, m_reg, mnA, alA, C, thr); }
;   SLOAD(SO, 64); if constexpr (SD == 2) { if (2 < NT) SLOAD(SE, 2 * 64); }
;   SWAIT(); SWRITE(1, SO); __syncthreads();
	v_mfma_f32_32x32x16_bf16 v[16:31], v[0:3], v[154:157], v[16:31]
	s_mov_b32 s12, s8
	s_mov_b32 s13, s8
	s_mov_b32 s14, s8
	s_mov_b32 s15, s8
	s_mov_b32 s16, s8
	s_mov_b32 s17, s8
	s_mov_b32 s18, s8
	s_waitcnt lgkmcnt(2)
	v_mfma_f32_32x32x16_bf16 v[32:47], v[4:7], v[154:157], v[32:47]
	s_mov_b32 s19, s8
	s_mov_b32 s20, s8
	s_waitcnt vmcnt(5)
	ds_write_b128 v218, v[48:51] offset:16384
	s_waitcnt vmcnt(4)
	ds_write_b128 v218, v[52:55] offset:24576
	s_waitcnt vmcnt(3)
	ds_write_b128 v219, v[56:59] offset:58368
	s_waitcnt lgkmcnt(4)
	v_mfma_f32_32x32x16_bf16 v[16:31], v[8:11], v[158:161], v[16:31]
	s_mov_b32 s21, s8
	s_mov_b32 s22, s8
	s_mov_b32 s23, s8
	v_mov_b64_e32 v[0:1], s[8:9]
	v_mov_b64_e32 v[14:15], s[22:23]
	v_mov_b64_e32 v[2:3], s[10:11]
	v_mov_b64_e32 v[4:5], s[12:13]
	s_waitcnt lgkmcnt(3)
	v_mfma_f32_32x32x16_bf16 v[32:47], v[60:63], v[158:161], v[32:47]
	s_nop 2
	v_max_f32_e32 v60, v17, v17
	v_max_f32_e32 v61, v16, v16
	v_max_f32_e32 v60, v61, v60
	v_max3_f32 v60, v60, v18, v19
	v_max3_f32 v60, v60, v20, v21
	v_max3_f32 v60, v60, v22, v23
	v_max3_f32 v60, v60, v24, v25
	v_max3_f32 v60, v60, v26, v27
	v_max3_f32 v60, v60, v28, v29
	v_max3_f32 v60, v60, v30, v31
	v_max3_f32 v60, v60, v32, v33
	v_max3_f32 v60, v60, v34, v35
	v_max3_f32 v60, v60, v36, v37
	v_max3_f32 v60, v60, v38, v39
	v_max3_f32 v60, v60, v40, v41
	v_max3_f32 v60, v60, v42, v43
	v_max3_f32 v60, v60, v44, v45
	v_max3_f32 v60, v60, v46, v47
	v_mov_b32_e32 v61, v60
	s_nop 1
	v_permlane32_swap_b32_e32 v60, v61
	v_max_f32_e32 v48, v61, v61
	v_max_f32_e32 v49, v60, v60
	v_max_f32_e32 v48, v49, v48
	v_sub_f32_e32 v16, v16, v48
	v_exp_f32_e32 v175, v16
	v_sub_f32_e32 v16, v17, v48
	v_exp_f32_e32 v176, v16
	v_sub_f32_e32 v16, v18, v48
	v_exp_f32_e32 v177, v16
	v_sub_f32_e32 v16, v19, v48
	v_exp_f32_e32 v178, v16
	v_sub_f32_e32 v16, v20, v48
	v_exp_f32_e32 v179, v16
	v_sub_f32_e32 v16, v21, v48
	v_exp_f32_e32 v181, v16
	v_sub_f32_e32 v16, v22, v48
	v_exp_f32_e32 v183, v16
	v_sub_f32_e32 v16, v23, v48
	v_exp_f32_e32 v185, v16
	v_sub_f32_e32 v16, v24, v48
	v_exp_f32_e32 v180, v16
	v_sub_f32_e32 v16, v25, v48
	v_exp_f32_e32 v182, v16
	v_sub_f32_e32 v16, v26, v48
	v_exp_f32_e32 v184, v16
	v_sub_f32_e32 v16, v27, v48
	v_exp_f32_e32 v227, v16
	v_sub_f32_e32 v16, v28, v48
	v_exp_f32_e32 v228, v16
	v_sub_f32_e32 v16, v29, v48
	v_sub_f32_e32 v31, v31, v48
	v_exp_f32_e32 v229, v16
	v_sub_f32_e32 v16, v30, v48
	v_exp_f32_e32 v174, v31
	v_exp_f32_e32 v230, v16
	v_add_f32_e32 v222, 0, v48
	v_mov_b64_e32 v[6:7], s[14:15]
	v_mov_b64_e32 v[8:9], s[16:17]
	v_mov_b64_e32 v[10:11], s[18:19]
	v_mov_b64_e32 v[12:13], s[20:21]
	v_xor_b32_e32 v80, 0x80000000, v222
	v_sub_f32_e32 v111, v47, v48
	v_sub_f32_e32 v110, v46, v48
	v_sub_f32_e32 v109, v45, v48
	v_sub_f32_e32 v108, v44, v48
	v_sub_f32_e32 v107, v43, v48
	v_sub_f32_e32 v106, v42, v48
	v_sub_f32_e32 v105, v41, v48
	v_sub_f32_e32 v104, v40, v48
	v_sub_f32_e32 v103, v39, v48
	v_sub_f32_e32 v102, v38, v48
	v_sub_f32_e32 v101, v37, v48
	v_sub_f32_e32 v100, v36, v48
	v_sub_f32_e32 v99, v35, v48
	v_sub_f32_e32 v98, v34, v48
	v_sub_f32_e32 v97, v33, v48
	v_sub_f32_e32 v96, v32, v48
	v_mov_b64_e32 v[62:63], v[14:15]
	v_mov_b64_e32 v[46:47], v[14:15]
	v_mov_b64_e32 v[30:31], v[14:15]
	s_mov_b32 s58, 1
	s_mov_b32 s59, 2
	v_cmp_gt_u32_e64 s[6:7], 32, v64
	v_lshl_add_u32 v199, v189, 2, v191
	v_mov_b32_e32 v201, 0
	v_mov_b32_e32 v223, 1.0
	s_mov_b32 s12, 0x80000
	s_mov_b32 s13, 0x48000
	v_mov_b64_e32 v[60:61], v[12:13]
	v_mov_b64_e32 v[58:59], v[10:11]
	v_mov_b64_e32 v[56:57], v[8:9]
	v_mov_b64_e32 v[54:55], v[6:7]
	v_mov_b64_e32 v[52:53], v[4:5]
	v_mov_b64_e32 v[50:51], v[2:3]
	v_mov_b64_e32 v[48:49], v[0:1]
	v_mov_b64_e32 v[44:45], v[12:13]
	v_mov_b64_e32 v[42:43], v[10:11]
	v_mov_b64_e32 v[40:41], v[8:9]
	v_mov_b64_e32 v[38:39], v[6:7]
	v_mov_b64_e32 v[36:37], v[4:5]
	v_mov_b64_e32 v[34:35], v[2:3]
	v_mov_b64_e32 v[32:33], v[0:1]
	v_mov_b64_e32 v[28:29], v[12:13]
	v_mov_b64_e32 v[26:27], v[10:11]
	v_mov_b64_e32 v[24:25], v[8:9]
	v_mov_b64_e32 v[22:23], v[6:7]
	v_mov_b64_e32 v[20:21], v[4:5]
	v_mov_b64_e32 v[18:19], v[2:3]
	v_mov_b64_e32 v[16:17], v[0:1]
	s_mov_b32 s14, 1
	v_mov_b32_e32 v81, v80
	v_mov_b32_e32 v82, v80
	v_mov_b32_e32 v83, v80
	v_mov_b32_e32 v84, v80
	v_mov_b32_e32 v85, v80
	v_mov_b32_e32 v86, v80
	v_mov_b32_e32 v87, v80
	v_mov_b32_e32 v88, v80
	v_mov_b32_e32 v89, v80
	v_mov_b32_e32 v90, v80
	v_mov_b32_e32 v91, v80
	v_mov_b32_e32 v92, v80
	v_mov_b32_e32 v93, v80
	v_mov_b32_e32 v94, v80
	v_mov_b32_e32 v95, v80
	v_mov_b64_e32 v[64:65], v[80:81]
	v_mov_b64_e32 v[66:67], v[82:83]
	v_mov_b64_e32 v[68:69], v[84:85]
	v_mov_b64_e32 v[70:71], v[86:87]
	v_mov_b64_e32 v[72:73], v[88:89]
	v_mov_b64_e32 v[74:75], v[90:91]
	v_mov_b64_e32 v[76:77], v[92:93]
	v_mov_b64_e32 v[78:79], v[94:95]
	s_waitcnt lgkmcnt(0)
	s_mov_b32 s15, s58
	s_mov_b32 s58, s8
	s_mul_i32 s8, s15, 0x2400
	v_add_u32_e32 v215, s8, v221
; __device__ __forceinline__ void finishSM(f32x16& p0, f32x16& p1, float alpha, float& l_reg, bf16x8& pa0, bf16x8& pa1, bf16x8& pa2, bf16x8& pa3) {
; #pragma unroll
;   for (int r = 0; r < 16; ++r) p1[r] = __builtin_amdgcn_exp2f(p1[r]);
;   float ps = 0;
; #pragma unroll
;   for (int r = 0; r < 16; ++r) ps += p0[r];
; #pragma unroll
;   for (int r = 0; r < 16; ++r) ps += p1[r];
;   { auto rr = __builtin_amdgcn_permlane32_swap(__float_as_uint(ps), __float_as_uint(ps), false, false);
;     ps = __uint_as_float(rr[0]) + __uint_as_float(rr[1]); }
;   l_reg = l_reg * alpha + ps;
;     ...
;   PK4(p0, 0, pa0); PK4(p0, 8, pa1); PK4(p1, 0, pa2); PK4(p1, 8, pa3);
;     ...
; }
; template <int NQK>
; __device__ __forceinline__ void qkt(f32x16& p0, f32x16& p1, const char* Ks, const bf16x8* qr, int r32, int hi) {
;   constexpr int KROW = NQK * 32 + 16;
;   p0 = f32x16{}; p1 = f32x16{};
; #pragma unroll
;   for (int d0 = 0; d0 < NQK; ++d0) { const int cb = (d0 * 16 + hi * 8) * 2;
;     bf16x8 b0 = *reinterpret_cast<const bf16x8*>(Ks + r32 * KROW + cb);
;     bf16x8 b1 = *reinterpret_cast<const bf16x8*>(Ks + (32 + r32) * KROW + cb);
;     p0 = __builtin_amdgcn_mfma_f32_32x32x16_bf16(b0, qr[d0], p0, 0, 0, 0);
;     p1 = __builtin_amdgcn_mfma_f32_32x32x16_bf16(b1, qr[d0], p1, 0, 0, 0); }
; }
; template <int NQK>
; __device__ __forceinline__ void qkt_mi(f32x16& p0, f32x16& p1, const char* Ks, const bf16x8* qr, int r32, int hi, const f32x16& minit) {
;   constexpr int KROW = NQK * 32 + 16;
; #pragma unroll
;   for (int d0 = 0; d0 < NQK; ++d0) { const int cb = (d0 * 16 + hi * 8) * 2;
;     bf16x8 b0 = *reinterpret_cast<const bf16x8*>(Ks + r32 * KROW + cb);
;     bf16x8 b1 = *reinterpret_cast<const bf16x8*>(Ks + (32 + r32) * KROW + cb);
;     if (d0 == 0) { p0 = __builtin_amdgcn_mfma_f32_32x32x16_bf16(b0, qr[0], minit, 0, 0, 0); p1 = __builtin_amdgcn_mfma_f32_32x32x16_bf16(b1, qr[0], minit, 0, 0, 0); }
;     else { p0 = __builtin_amdgcn_mfma_f32_32x32x16_bf16(b0, qr[d0], p0, 0, 0, 0); p1 = __builtin_amdgcn_mfma_f32_32x32x16_bf16(b1, qr[d0], p1, 0, 0, 0); } }
; }
; __device__ __forceinline__ void decide_mi(f32x16& p0, f32x16& p1, f32x16& minit, float& M, float& alpha, const float thr2, const bool first) {
;   float pmax = p0[0];
; #pragma unroll
;   for (int r = 1; r < 16; ++r) pmax = fmaxf(pmax, p0[r]);
; #pragma unroll
;   for (int r = 0; r < 16; ++r) pmax = fmaxf(pmax, p1[r]);
.LBB0_1286:
	s_barrier
	ds_read_b128 v[232:235], v215 offset:53760
	ds_read_b128 v[112:115], v215 offset:49152
	ds_read_b128 v[236:239], v215 offset:49184
	v_exp_f32_e32 v96, v96
	v_exp_f32_e32 v97, v97
	v_exp_f32_e32 v99, v99
	s_waitcnt lgkmcnt(1)
	v_mfma_f32_32x32x16_bf16 v[128:143], v[112:115], v[146:149], v[80:95]
	s_waitcnt lgkmcnt(0)
	v_mfma_f32_32x32x16_bf16 v[128:143], v[236:239], v[150:153], v[128:143]
	v_exp_f32_e32 v100, v100
	v_exp_f32_e32 v101, v101
	v_exp_f32_e32 v102, v102
	v_exp_f32_e32 v103, v103
	v_mfma_f32_32x32x16_bf16 v[112:127], v[232:235], v[146:149], v[80:95]
	ds_read_b128 v[232:235], v215 offset:53792
	s_waitcnt lgkmcnt(0)
	v_mfma_f32_32x32x16_bf16 v[112:127], v[232:235], v[150:153], v[112:127]
	ds_read_b128 v[232:235], v215 offset:53824
	ds_read_b128 v[236:239], v215 offset:49216
	s_waitcnt lgkmcnt(0)
	v_mfma_f32_32x32x16_bf16 v[128:143], v[236:239], v[154:157], v[128:143]
	v_mfma_f32_32x32x16_bf16 v[112:127], v[232:235], v[154:157], v[112:127]
	ds_read_b128 v[232:235], v215 offset:53856
	ds_read_b128 v[236:239], v215 offset:49248
	v_exp_f32_e32 v215, v98
	v_exp_f32_e32 v98, v104
	v_exp_f32_e32 v104, v105
	v_exp_f32_e32 v105, v106
	v_exp_f32_e32 v106, v107
	v_exp_f32_e32 v107, v108
	v_exp_f32_e32 v108, v109
	v_exp_f32_e32 v109, v110
	v_exp_f32_e32 v110, v111
	v_add_f32_e32 v111, 0, v175
	v_add_f32_e32 v111, v176, v111
	v_add_f32_e32 v111, v177, v111
	v_add_f32_e32 v111, v178, v111
	v_add_f32_e32 v111, v179, v111
	v_add_f32_e32 v111, v181, v111
	v_add_f32_e32 v111, v183, v111
	v_add_f32_e32 v111, v185, v111
	v_add_f32_e32 v111, v180, v111
	v_add_f32_e32 v111, v182, v111
	v_add_f32_e32 v111, v184, v111
	v_add_f32_e32 v111, v227, v111
	v_add_f32_e32 v111, v228, v111
	v_add_f32_e32 v111, v229, v111
	v_add_f32_e32 v111, v230, v111
	v_add_f32_e32 v111, v174, v111
	v_add_f32_e32 v111, v96, v111
	v_add_f32_e32 v111, v97, v111
	v_add_f32_e32 v111, v215, v111
	v_add_f32_e32 v111, v99, v111
	v_add_f32_e32 v111, v100, v111
	v_add_f32_e32 v111, v101, v111
	v_add_f32_e32 v111, v102, v111
	s_waitcnt lgkmcnt(0)
	v_mfma_f32_32x32x16_bf16 v[128:143], v[236:239], v[158:161], v[128:143]
	v_add_f32_e32 v111, v103, v111
	v_add_f32_e32 v111, v98, v111
	v_add_f32_e32 v111, v104, v111
	v_add_f32_e32 v111, v105, v111
	v_add_f32_e32 v111, v106, v111
	v_add_f32_e32 v111, v107, v111
	v_add_f32_e32 v111, v108, v111
	v_add_f32_e32 v111, v109, v111
	v_add_f32_e32 v224, v110, v111
	s_nop 2
	v_max_f32_e32 v111, v129, v129
	v_max_f32_e32 v226, v128, v128
	v_mfma_f32_32x32x16_bf16 v[112:127], v[232:235], v[158:161], v[112:127]
	v_max_f32_e32 v111, v226, v111
	v_max3_f32 v111, v111, v130, v131
	v_max3_f32 v111, v111, v132, v133
	v_max3_f32 v111, v111, v134, v135
	v_max3_f32 v111, v111, v136, v137
	v_max3_f32 v111, v111, v138, v139
	v_max3_f32 v111, v111, v140, v141
	v_max3_f32 v111, v111, v142, v143
	s_nop 3
	v_max3_f32 v111, v111, v112, v113
	v_max3_f32 v111, v111, v114, v115
	v_max3_f32 v111, v111, v116, v117
	v_max3_f32 v111, v111, v118, v119
	v_max3_f32 v111, v111, v120, v121
	v_max3_f32 v111, v111, v122, v123
	v_max3_f32 v111, v111, v124, v125
	v_max3_f32 v111, v111, v126, v127
	v_mov_b32_e32 v226, v111
	s_nop 1
	v_permlane32_swap_b32_e32 v111, v226
	v_max_f32_e32 v226, v226, v226
	v_max_f32_e32 v111, v111, v111
	v_max_f32_e32 v111, v111, v226
	v_mov_b32_e32 v225, v224
	v_cmp_ge_f32_e32 vcc, s42, v111
	s_nop 0
	v_permlane32_swap_b32_e32 v224, v225
	s_cmp_eq_u64 vcc, exec
	s_cbranch_scc0 .LBB0_1301
	v_mov_b32_e32 v226, 1.0

; #define SBAR() __builtin_amdgcn_sched_barrier(0)
; #define SWRITE(b, i) do { STG_T() const int _sv = VSTV(), _sk = LDSK(); *(u32x4*)(V_lds + (b) * SHM_V + _sv) = sr_[i].vs0; *(u32x4*)(V_lds + (b) * SHM_V + _sv + 8192) = sr_[i].vs1; \
;     _Pragma("unroll") for (int _p = 0; _p < NP; ++_p) *(u32x4*)(K_lds + (b) * KT + _sk + _p * 128) = sr_[i].ks[_p]; } while (0)
; #define SWAIT() do { if constexpr (SD == 2) { if constexpr (NP == 1) asm volatile("s_waitcnt vmcnt(3)" ::: "memory"); else asm volatile("s_waitcnt vmcnt(5)" ::: "memory"); } else asm volatile("s_waitcnt vmcnt(0)" ::: "memory"); } while (0)
; #define RESC(a) do { if (__any((a) < 1.f)) { if (hi == 0) al_l[r32] = (a); asm volatile("s_waitcnt lgkmcnt(0)" ::: "memory"); \
;     _Pragma("unroll") for (int d = 0; d < 4; ++d) _Pragma("unroll") for (int r = 0; r < 16; ++r) o[d][r] *= al_l[crow(r, hi)]; } } while (0)
; #define QKT(P0, P1, KS) do { if constexpr (MI) qkt_mi<NQK>(P0, P1, KS, qr, r32, hi, minit); else qkt<NQK>(P0, P1, KS, qr, r32, hi); } while (0)
; #define DECIDE(P0, P1, MN, AL) do { if constexpr (MI) decide_mi(P0, P1, minit, Mref, AL, thr2, false); else decideSM(P0, P1, m_reg, MN, AL, C, thr); } while (0)
; #define PVSM(VB, P0, P1, MN) do { if constexpr (MI) pv_mi(o, VB, pa0, pa1, pa2, pa3, P0); else pv_sm(o, VB, pa0, pa1, pa2, pa3, P0, P1, C, MN); } while (0)
; #define ROT() do { const int _r = rp; rp = rc; rc = rn; rn = _r; } while (0)
; template <int NQK, int SD, bool MI> ...
;     ...
;   for (int j = 1; j + 1 < NT; j += 2) {
;     SBAR(); QKT(pB0, pB1, K_lds + rc * KT);
;     finishSM(pA0, pA1, alA, l_reg, pa0, pa1, pa2, pa3); DECIDE(pB0, pB1, mnB, alB); SBAR();
;     SLOAD(SO, (j + SD) * 64); SBAR();
;     PVSM(vb0 + rp * SHM_V, pB0, pB1, mnB);
;     SWAIT(); SWRITE(rn, SE);
;     RESC(alB); __syncthreads(); ROT();
;     SBAR(); QKT(pA0, pA1, K_lds + rc * KT);
;     finishSM(pB0, pB1, alB, l_reg, pa0, pa1, pa2, pa3); DECIDE(pA0, pA1, mnA, alA); SBAR();
;     if (SD == 1 || j + 3 < NT) SLOAD(SE, (j + 1 + SD) * 64); SBAR();
;     PVSM(vb0 + rp * SHM_V, pA0, pA1, mnA);
;     SWAIT(); SWRITE(rn, SO);
;     RESC(alA); __syncthreads(); ROT();
;   }
.LBB0_1299:
	v_exp_f32_e32 v175, v128
	v_exp_f32_e32 v176, v129
	v_exp_f32_e32 v177, v130
	v_exp_f32_e32 v178, v131
	v_exp_f32_e32 v179, v132
	v_exp_f32_e32 v181, v133
	v_exp_f32_e32 v183, v134
	v_exp_f32_e32 v185, v135
	v_exp_f32_e32 v180, v136
	v_exp_f32_e32 v182, v137
	v_exp_f32_e32 v184, v138
	v_exp_f32_e32 v227, v139
	v_exp_f32_e32 v228, v140
	v_exp_f32_e32 v229, v141
	v_exp_f32_e32 v230, v142
	v_exp_f32_e32 v174, v143
	v_add_f32_e32 v115, v224, v225
	v_fmac_f32_e32 v115, v223, v201
	v_add_f32_e32 v201, v113, v114
	v_fmac_f32_e32 v201, v115, v226
	s_add_i32 s14, s14, 2
	s_add_i32 s12, s12, 0x40000
	s_add_i32 s13, s13, 0x20000
	s_and_b64 vcc, exec, s[8:9]
	s_waitcnt lgkmcnt(0)
	s_cbranch_vccnz .Ldat_exitbar
	s_mov_b32 s8, s59
	s_mov_b32 s59, s15
	v_mov_b32_e32 v223, v112
	s_mov_b32 s15, s58
	s_mov_b32 s58, s8
	s_mul_i32 s8, s15, 0x2400
	v_add_u32_e32 v215, s8, v221
	s_branch .LBB0_1286
.Ldat_exitbar:
	s_barrier
	s_branch .LBB0_1303

; #define SWRITE(b, i) do { STG_T() const int _sv = VSTV(), _sk = LDSK(); *(u32x4*)(V_lds + (b) * SHM_V + _sv) = sr_[i].vs0; *(u32x4*)(V_lds + (b) * SHM_V + _sv + 8192) = sr_[i].vs1; \
;     _Pragma("unroll") for (int _p = 0; _p < NP; ++_p) *(u32x4*)(K_lds + (b) * KT + _sk + _p * 128) = sr_[i].ks[_p]; } while (0)
; #define SWAIT() do { if constexpr (SD == 2) { if constexpr (NP == 1) asm volatile("s_waitcnt vmcnt(3)" ::: "memory"); else asm volatile("s_waitcnt vmcnt(5)" ::: "memory"); } else asm volatile("s_waitcnt vmcnt(0)" ::: "memory"); } while (0)
; template <int NQK>
; __device__ __forceinline__ void qkt(f32x16& p0, f32x16& p1, const char* Ks, const bf16x8* qr, int r32, int hi) {
;   constexpr int KROW = NQK * 32 + 16;
;   p0 = f32x16{}; p1 = f32x16{};
; #pragma unroll
;   for (int d0 = 0; d0 < NQK; ++d0) { const int cb = (d0 * 16 + hi * 8) * 2;
;     bf16x8 b0 = *reinterpret_cast<const bf16x8*>(Ks + r32 * KROW + cb);
;     bf16x8 b1 = *reinterpret_cast<const bf16x8*>(Ks + (32 + r32) * KROW + cb);
;     p0 = __builtin_amdgcn_mfma_f32_32x32x16_bf16(b0, qr[d0], p0, 0, 0, 0);
;     p1 = __builtin_amdgcn_mfma_f32_32x32x16_bf16(b1, qr[d0], p1, 0, 0, 0); }
; }
; template <int NQK, int SD, bool MI> ...
;     ...
;   SLOAD(SE, 0); asm volatile("s_waitcnt vmcnt(0)" ::: "memory"); SWRITE(0, SE); __syncthreads();
;   if constexpr (MI) { qkt_mi<NQK>(pA0, pA1, K_lds, qr, r32, hi, minit); decide_mi(pA0, pA1, minit, Mref, alA, thr2, true);
; #pragma unroll
;     for (int r = 0; r < 16; ++r) pA0[r] = __builtin_amdgcn_exp2f(pA0[r]); }
;   else { qkt<NQK>(pA0, pA1, K_lds, qr, r32, hi); partialSM(pA0, pA1, m_reg, mnA, alA, C, thr); }
;   SLOAD(SO, 64); if constexpr (SD == 2) { if (2 < NT) SLOAD(SE, 2 * 64); }
;   SWAIT(); SWRITE(1, SO); __syncthreads();
.LBB0_2538:
	s_add_u32 s36, s26, s7
	s_addc_u32 s7, s27, 0
	s_lshl_b32 s34, s6, 7
	s_lshl_b32 s6, s6, 8
	v_ashrrev_i32_e32 v22, 4, v0
	v_lshlrev_b32_e32 v23, 3, v0
	s_add_u32 s28, s48, s6
	v_and_b32_e32 v2, 0x78, v23
	v_lshlrev_b32_e32 v3, 10, v22
	s_addc_u32 s6, s49, 0
	v_lshl_or_b32 v170, v2, 1, v3
	v_ashrrev_i32_e32 v24, 3, v0
	v_lshlrev_b32_e32 v2, 4, v0
	v_and_b32_e32 v25, 0x70, v2
	v_mul_lo_u32 v2, v24, s64
	s_and_b32 s29, s6, 0xffff
	v_or_b32_e32 v171, v25, v2
	s_and_b32 s37, s7, 0xffff
	s_mov_b32 s38, s30
	s_mov_b32 s39, s31
	s_waitcnt lgkmcnt(0)
	s_barrier
	buffer_load_dwordx4 v[2:5], v170, s[28:31], 0 offen
	buffer_load_dwordx4 v[6:9], v170, s[28:31], s74 offen
	buffer_load_dwordx4 v[10:13], v171, s[36:39], 0 offen
	buffer_load_dwordx4 v[14:17], v171, s[36:39], 0 offen offset:128
	buffer_load_dwordx4 v[18:21], v171, s[36:39], 0 offen offset:256
	v_bfe_u32 v27, v23, 5, 2
	v_lshlrev_b32_e32 v22, 5, v22
	v_and_b32_e32 v23, 24, v23
	v_lshrrev_b32_e32 v26, 5, v0
	v_and_or_b32 v22, v22, s70, v23
	v_and_b32_e32 v163, 31, v0
	v_and_or_b32 v26, v26, s41, v27
	v_lshlrev_b32_e32 v22, 1, v22
	v_mul_u32_u24_e32 v172, 0x190, v163
	v_lshl_or_b32 v22, v26, 9, v22
	v_mul_lo_u32 v24, v24, s72
	v_add3_u32 v174, 16, v172, v162
	v_add_u32_e32 v175, 16, v22
	v_add3_u32 v173, v24, v25, 16
	s_waitcnt vmcnt(0)
	s_mov_b32 s6, 0x18000
	v_and_b32_e32 v80, 63, v0
	v_and_b32_e32 v164, 0xffffffe0, v1
	v_and_b32_e32 v81, 0x3fffffc0, v0
	v_lshlrev_b32_e32 v82, 3, v80
	v_and_b32_e32 v85, 0x100, v82
	s_mov_b32 s8, 0
	s_mov_b32 s9, s8
	s_mov_b32 s10, s8
	s_mov_b32 s11, s8
	s_mov_b32 s12, s8
	s_mov_b32 s13, s8
	s_mov_b32 s14, s8
	s_mov_b32 s15, s8
	s_mov_b32 s16, s8
	s_mov_b32 s17, s8
	s_mov_b32 s18, s8
	s_mov_b32 s19, s8
	s_mov_b32 s20, s8
	s_mov_b32 s21, s8
	s_mov_b32 s22, s8
	s_mov_b32 s23, s8
	s_mov_b32 s44, 1
	s_mov_b32 s51, 2
	s_mov_b32 s45, -1
	v_or_b32_e32 v176, 0x80, v171
	v_or_b32_e32 v177, 0x100, v171
	v_mov_b32_e32 v167, 0
	s_waitcnt vmcnt(4)
	ds_write_b128 v175, v[2:5]
	s_waitcnt vmcnt(3)
	ds_write_b128 v175, v[6:9] offset:8192
	s_waitcnt vmcnt(2)
	ds_write_b128 v173, v[10:13] offset:49152
	s_waitcnt vmcnt(1)
	ds_write_b128 v173, v[14:17] offset:49280
	s_waitcnt vmcnt(0)
	ds_write_b128 v173, v[18:21] offset:49408
	s_waitcnt lgkmcnt(0)
	s_barrier
	ds_read_b128 v[2:5], v174 offset:49152
	ds_read_b128 v[6:9], v174 offset:49184
	s_waitcnt lgkmcnt(1)
	v_mfma_f32_32x32x16_bf16 v[32:47], v[2:5], v[140:143], 0
	ds_read_b128 v[2:5], v174 offset:61952
	ds_read_b128 v[10:13], v174 offset:61984
	s_waitcnt lgkmcnt(1)
	v_mfma_f32_32x32x16_bf16 v[16:31], v[2:5], v[140:143], 0
	v_mfma_f32_32x32x16_bf16 v[32:47], v[6:9], v[136:139], v[32:47]
	ds_read_b128 v[2:5], v174 offset:49216
	ds_read_b128 v[6:9], v174 offset:49248
	s_waitcnt lgkmcnt(2)
	v_mfma_f32_32x32x16_bf16 v[16:31], v[10:13], v[136:139], v[16:31]
	s_waitcnt lgkmcnt(1)
	v_mfma_f32_32x32x16_bf16 v[32:47], v[2:5], v[132:135], v[32:47]
	ds_read_b128 v[2:5], v174 offset:62016
	ds_read_b128 v[10:13], v174 offset:62048
	s_waitcnt lgkmcnt(1)
	v_mfma_f32_32x32x16_bf16 v[16:31], v[2:5], v[132:135], v[16:31]
	v_mfma_f32_32x32x16_bf16 v[32:47], v[6:9], v[128:131], v[32:47]
	ds_read_b128 v[2:5], v174 offset:49280
	ds_read_b128 v[6:9], v174 offset:49312
	s_waitcnt lgkmcnt(2)
	v_mfma_f32_32x32x16_bf16 v[16:31], v[10:13], v[128:131], v[16:31]
	s_waitcnt lgkmcnt(1)
	v_mfma_f32_32x32x16_bf16 v[32:47], v[2:5], v[124:127], v[32:47]
	ds_read_b128 v[2:5], v174 offset:62080
	ds_read_b128 v[10:13], v174 offset:62112
	s_waitcnt lgkmcnt(1)
	v_mfma_f32_32x32x16_bf16 v[16:31], v[2:5], v[124:127], v[16:31]
	v_mfma_f32_32x32x16_bf16 v[32:47], v[6:9], v[120:123], v[32:47]
	ds_read_b128 v[2:5], v174 offset:49344
	ds_read_b128 v[6:9], v174 offset:49376
	s_waitcnt lgkmcnt(2)
	v_mfma_f32_32x32x16_bf16 v[16:31], v[10:13], v[120:123], v[16:31]
	s_waitcnt lgkmcnt(1)
	v_mfma_f32_32x32x16_bf16 v[32:47], v[2:5], v[116:119], v[32:47]
	ds_read_b128 v[2:5], v174 offset:62144
	ds_read_b128 v[10:13], v174 offset:62176
	buffer_load_dwordx4 v[48:51], v170, s[28:31], s75 offen
	buffer_load_dwordx4 v[52:55], v170, s[28:31], s6 offen
	buffer_load_dwordx4 v[56:59], v171, s[36:39], s6 offen
	buffer_load_dwordx4 v[60:63], v171, s[36:39], s6 offen offset:128
	buffer_load_dwordx4 v[64:67], v171, s[36:39], s6 offen offset:256
	s_add_i32 s6, 16, 0x1ec00
	v_lshl_add_u32 v165, v81, 2, s6
	s_cmp_lg_u32 16, -1
	s_waitcnt lgkmcnt(1)
	v_mfma_f32_32x32x16_bf16 v[16:31], v[2:5], v[116:119], v[16:31]
	ds_read_b128 v[2:5], v174 offset:49408
	s_cselect_b32 s6, 16, 0
	v_lshl_add_u32 v166, v163, 2, v165
	v_mfma_f32_32x32x16_bf16 v[32:47], v[6:9], v[112:115], v[32:47]
	s_waitcnt lgkmcnt(0)
	v_mfma_f32_32x32x16_bf16 v[32:47], v[2:5], v[108:111], v[32:47]
	v_lshlrev_b32_e32 v4, 4, v80
	v_lshlrev_b32_e32 v5, 1, v80
	v_and_b32_e32 v83, 0xc0, v4
	v_and_b32_e32 v84, 32, v5
	v_mfma_f32_32x32x16_bf16 v[16:31], v[10:13], v[112:115], v[16:31]
	ds_read_b128 v[6:9], v174 offset:62208
	ds_read_b128 v[10:13], v174 offset:49440
	ds_read_b128 v[0:3], v174 offset:62240
	ds_read_b128 v[68:71], v174 offset:49472
	ds_read_b128 v[72:75], v174 offset:62272
	ds_read_b128 v[76:79], v174 offset:49504
	s_waitcnt lgkmcnt(4)
	v_mfma_f32_32x32x16_bf16 v[32:47], v[10:13], v[104:107], v[32:47]
	v_mfma_f32_32x32x16_bf16 v[16:31], v[6:9], v[108:111], v[16:31]
	s_waitcnt lgkmcnt(2)
	v_mfma_f32_32x32x16_bf16 v[32:47], v[68:71], v[100:103], v[32:47]
	v_and_or_b32 v68, v82, 24, v83
	v_or3_b32 v81, v68, v84, v85
	ds_read_b128 v[68:71], v174 offset:62304
	v_add_u32_e32 v82, 0x12400, v173
	s_waitcnt vmcnt(0)
	s_waitcnt vmcnt(4)
	ds_write_b128 v175, v[48:51] offset:16384
	s_waitcnt vmcnt(3)
	ds_write_b128 v175, v[52:55] offset:24576
	s_waitcnt vmcnt(2)
	ds_write_b128 v82, v[56:59]
	v_mfma_f32_32x32x16_bf16 v[16:31], v[0:3], v[104:107], v[16:31]
	v_mov_b64_e32 v[0:1], s[8:9]
	v_mov_b64_e32 v[14:15], s[22:23]
	v_mov_b64_e32 v[2:3], s[10:11]
	v_mov_b64_e32 v[4:5], s[12:13]
	v_mov_b64_e32 v[6:7], s[14:15]
	v_mov_b64_e32 v[8:9], s[16:17]
	v_mov_b64_e32 v[10:11], s[18:19]
	s_waitcnt lgkmcnt(4)
	v_mfma_f32_32x32x16_bf16 v[32:47], v[76:79], v[96:99], v[32:47]
	v_mov_b64_e32 v[12:13], s[20:21]
	s_waitcnt vmcnt(1)
	ds_write_b128 v82, v[60:63] offset:128
	s_waitcnt vmcnt(0)
	ds_write_b128 v82, v[64:67] offset:256
	v_add_u32_e32 v168, s6, v81
	v_cmp_gt_u32_e64 s[6:7], 32, v80
	s_mov_b32 s12, 0x30000
	s_mov_b32 s13, 0x38000
	s_waitcnt lgkmcnt(0)
	v_mfma_f32_32x32x16_bf16 v[16:31], v[72:75], v[100:103], v[16:31]
	s_nop 0
	v_max_f32_e32 v48, v33, v33
	v_max_f32_e32 v49, v32, v32
	v_max_f32_e32 v48, v49, v48
	v_max3_f32 v48, v48, v34, v35
	v_max3_f32 v48, v48, v36, v37
	v_max3_f32 v48, v48, v38, v39
	v_max3_f32 v48, v48, v40, v41
	v_mfma_f32_32x32x16_bf16 v[16:31], v[68:71], v[96:99], v[16:31]
	v_max3_f32 v48, v48, v42, v43
	v_max3_f32 v48, v48, v44, v45
	v_max3_f32 v48, v48, v46, v47
	s_barrier
; __device__ __forceinline__ void partialSM(f32x16& p0, f32x16& p1, float& m_reg, float& mn, float& alpha, const float C, const float thr) {
;   float pmax = p0[0];
; #pragma unroll
;   for (int r = 1; r < 16; ++r) pmax = fmaxf(pmax, p0[r]);
; #pragma unroll
;   for (int r = 0; r < 16; ++r) pmax = fmaxf(pmax, p1[r]);
;   { auto rr = __builtin_amdgcn_permlane32_swap(__float_as_uint(pmax), __float_as_uint(pmax), false, false);
;     pmax = fmaxf(__uint_as_float(rr[0]), __uint_as_float(rr[1])); }
;   if (__builtin_expect(__all(pmax - m_reg <= thr), 1)) { mn = m_reg; alpha = 1.f; }
;   else { mn = fmaxf(m_reg, pmax); alpha = __builtin_amdgcn_exp2f((m_reg - mn) * C); m_reg = mn; }
;   const float mnC = -mn * C;
; #pragma unroll
;   for (int r = 0; r < 16; ++r) p0[r] = fmaf(p0[r], C, mnC);
; #pragma unroll
;   for (int r = 0; r < 16; ++r) p1[r] = fmaf(p1[r], C, mnC);
; #pragma unroll
;   for (int r = 0; r < 16; ++r) p0[r] = __builtin_amdgcn_exp2f(p0[r]);
; }
	s_nop 7
	v_max3_f32 v48, v48, v16, v17
	v_max3_f32 v48, v48, v18, v19
	v_max3_f32 v48, v48, v20, v21
	v_max3_f32 v48, v48, v22, v23
	v_max3_f32 v48, v48, v24, v25
	v_max3_f32 v48, v48, v26, v27
	v_max3_f32 v48, v48, v28, v29
	v_max3_f32 v48, v48, v30, v31
	v_mov_b32_e32 v49, v48
	s_nop 1
	v_permlane32_swap_b32_e32 v48, v49
	v_max_f32_e32 v49, v49, v49
	v_max_f32_e32 v48, v48, v48
	v_max_f32_e32 v48, v48, v49
	v_add_f32_e32 v49, 0x7149f2ca, v48
	v_cmp_ge_f32_e32 vcc, s56, v49
	s_cmp_eq_u64 vcc, exec
	v_max_f32_e32 v50, 0xf149f2ca, v48
	s_cselect_b64 vcc, -1, 0
	v_cndmask_b32_e32 v178, v50, v213, vcc
	v_mul_f32_e32 v48, 0xbdd53b94, v178
	v_pk_fma_f32 v[154:155], v[22:23], s[92:93], v[48:49] op_sel_hi:[1,0,0]
	v_sub_f32_e32 v22, 0xf149f2ca, v50
	v_mul_f32_e32 v22, 0x3dd53b94, v22
	v_exp_f32_e32 v22, v22
	v_fmamk_f32 v32, v32, 0x3dd53b94, v48
	v_fmamk_f32 v33, v33, 0x3dd53b94, v48
	v_fmamk_f32 v34, v34, 0x3dd53b94, v48
	v_fmamk_f32 v35, v35, 0x3dd53b94, v48
	v_fmamk_f32 v36, v36, 0x3dd53b94, v48
	v_fmamk_f32 v37, v37, 0x3dd53b94, v48
	v_fmamk_f32 v38, v38, 0x3dd53b94, v48
	v_fmamk_f32 v39, v39, 0x3dd53b94, v48
	v_fmamk_f32 v40, v40, 0x3dd53b94, v48
	v_fmamk_f32 v41, v41, 0x3dd53b94, v48
	v_fmamk_f32 v42, v42, 0x3dd53b94, v48
	v_fmamk_f32 v43, v43, 0x3dd53b94, v48
	v_fmamk_f32 v44, v44, 0x3dd53b94, v48
	v_fmamk_f32 v45, v45, 0x3dd53b94, v48
	v_fmamk_f32 v46, v46, 0x3dd53b94, v48
	v_fmamk_f32 v47, v47, 0x3dd53b94, v48
	v_exp_f32_e32 v184, v32
	v_exp_f32_e32 v185, v33
	v_exp_f32_e32 v189, v34
	v_exp_f32_e32 v191, v35
	v_exp_f32_e32 v198, v36
	v_exp_f32_e32 v200, v37
	v_exp_f32_e32 v214, v38
	v_exp_f32_e32 v217, v39
	v_exp_f32_e32 v215, v40
	v_exp_f32_e32 v218, v41
	v_exp_f32_e32 v199, v42
	v_exp_f32_e32 v201, v43
	v_exp_f32_e32 v216, v44
	v_exp_f32_e32 v219, v45
	v_exp_f32_e32 v220, v46
	v_exp_f32_e32 v221, v47
	v_pk_fma_f32 v[146:147], v[30:31], s[92:93], v[48:49] op_sel_hi:[1,0,0]
	v_pk_fma_f32 v[148:149], v[28:29], s[92:93], v[48:49] op_sel_hi:[1,0,0]
	v_pk_fma_f32 v[150:151], v[26:27], s[92:93], v[48:49] op_sel_hi:[1,0,0]
	v_pk_fma_f32 v[152:153], v[24:25], s[92:93], v[48:49] op_sel_hi:[1,0,0]
	v_pk_fma_f32 v[156:157], v[20:21], s[92:93], v[48:49] op_sel_hi:[1,0,0]
	v_pk_fma_f32 v[158:159], v[18:19], s[92:93], v[48:49] op_sel_hi:[1,0,0]
	v_pk_fma_f32 v[160:161], v[16:17], s[92:93], v[48:49] op_sel_hi:[1,0,0]
	v_cndmask_b32_e64 v179, v22, 1.0, vcc
	v_mov_b64_e32 v[62:63], v[14:15]
	v_mov_b64_e32 v[46:47], v[14:15]
	v_mov_b64_e32 v[30:31], v[14:15]
	v_mov_b64_e32 v[60:61], v[12:13]
	v_mov_b64_e32 v[58:59], v[10:11]
	v_mov_b64_e32 v[56:57], v[8:9]
	v_mov_b64_e32 v[54:55], v[6:7]
	v_mov_b64_e32 v[52:53], v[4:5]
	v_mov_b64_e32 v[50:51], v[2:3]
	v_mov_b64_e32 v[48:49], v[0:1]
	v_mov_b64_e32 v[44:45], v[12:13]
	v_mov_b64_e32 v[42:43], v[10:11]
	v_mov_b64_e32 v[40:41], v[8:9]
	v_mov_b64_e32 v[38:39], v[6:7]
	v_mov_b64_e32 v[36:37], v[4:5]
	v_mov_b64_e32 v[34:35], v[2:3]
	v_mov_b64_e32 v[32:33], v[0:1]
	v_mov_b64_e32 v[28:29], v[12:13]
	v_mov_b64_e32 v[26:27], v[10:11]
	v_mov_b64_e32 v[24:25], v[8:9]
	v_mov_b64_e32 v[22:23], v[6:7]
	v_mov_b64_e32 v[20:21], v[4:5]
	v_mov_b64_e32 v[18:19], v[2:3]
	v_mov_b64_e32 v[16:17], v[0:1]
	s_mov_b32 s14, s44
	s_mov_b32 s44, s8
	s_mul_i32 s8, s14, 0x6400
	v_add_u32_e32 v169, s8, v174
	s_branch .Lmla_body

; #define PK4(P, BASE, OUT) do { u32x4 w = {cvtb(P[BASE + 0], P[BASE + 1]), cvtb(P[BASE + 2], P[BASE + 3]), \
;     cvtb(P[BASE + 4], P[BASE + 5]), cvtb(P[BASE + 6], P[BASE + 7])}; OUT = *reinterpret_cast<bf16x8*>(&w); } while (0)
; __device__ __forceinline__ void finishSM(f32x16& p0, f32x16& p1, float alpha, float& l_reg, bf16x8& pa0, bf16x8& pa1, bf16x8& pa2, bf16x8& pa3) {
; #pragma unroll
;   for (int r = 0; r < 16; ++r) p1[r] = __builtin_amdgcn_exp2f(p1[r]);
;   float ps = 0;
; #pragma unroll
;   for (int r = 0; r < 16; ++r) ps += p0[r];
; #pragma unroll
;   for (int r = 0; r < 16; ++r) ps += p1[r];
;   { auto rr = __builtin_amdgcn_permlane32_swap(__float_as_uint(ps), __float_as_uint(ps), false, false);
;     ps = __uint_as_float(rr[0]) + __uint_as_float(rr[1]); }
;   l_reg = l_reg * alpha + ps;
;     ...
;   PK4(p0, 0, pa0); PK4(p0, 8, pa1); PK4(p1, 0, pa2); PK4(p1, 8, pa3);
;     ...
; }
; template <int NQK>
; __device__ __forceinline__ void qkt(f32x16& p0, f32x16& p1, const char* Ks, const bf16x8* qr, int r32, int hi) {
;   constexpr int KROW = NQK * 32 + 16;
;   p0 = f32x16{}; p1 = f32x16{};
; #pragma unroll
;   for (int d0 = 0; d0 < NQK; ++d0) { const int cb = (d0 * 16 + hi * 8) * 2;
;     bf16x8 b0 = *reinterpret_cast<const bf16x8*>(Ks + r32 * KROW + cb);
;     bf16x8 b1 = *reinterpret_cast<const bf16x8*>(Ks + (32 + r32) * KROW + cb);
;     p0 = __builtin_amdgcn_mfma_f32_32x32x16_bf16(b0, qr[d0], p0, 0, 0, 0);
;     p1 = __builtin_amdgcn_mfma_f32_32x32x16_bf16(b1, qr[d0], p1, 0, 0, 0); }
; }
.Lmla_body:
	ds_read_b128 v[64:67], v169 offset:61952
	ds_read_b128 v[68:71], v169 offset:49152
	ds_read_b128 v[180:183], v169 offset:49184
	ds_read_b128 v[222:225], v169 offset:61984
	v_exp_f32_e32 v231, v146
	v_add_f32_e32 v146, 0, v184
	s_waitcnt lgkmcnt(2)
	v_mfma_f32_32x32x16_bf16 v[80:95], v[68:71], v[140:143], 0
	v_add_f32_e32 v146, v185, v146
	v_add_f32_e32 v146, v189, v146
	v_add_f32_e32 v146, v191, v146
	v_add_f32_e32 v146, v198, v146
	v_add_f32_e32 v146, v200, v146
	v_add_f32_e32 v146, v214, v146
	v_add_f32_e32 v146, v217, v146
	v_mfma_f32_32x32x16_bf16 v[64:79], v[64:67], v[140:143], 0
	v_add_f32_e32 v146, v215, v146
	v_add_f32_e32 v146, v218, v146
	v_add_f32_e32 v146, v199, v146
	v_add_f32_e32 v146, v201, v146
	v_add_f32_e32 v146, v216, v146
	v_add_f32_e32 v146, v219, v146
	v_add_f32_e32 v146, v220, v146
	s_waitcnt lgkmcnt(1)
	v_mfma_f32_32x32x16_bf16 v[80:95], v[180:183], v[136:139], v[80:95]
	v_add_f32_e32 v146, v221, v146
	v_exp_f32_e32 v229, v150
	v_exp_f32_e32 v226, v155
	v_exp_f32_e32 v227, v152
	v_exp_f32_e32 v228, v153
	v_exp_f32_e32 v230, v151
	v_exp_f32_e32 v148, v148
	s_waitcnt lgkmcnt(0)
	v_mfma_f32_32x32x16_bf16 v[64:79], v[222:225], v[136:139], v[64:79]
	ds_read_b128 v[180:183], v169 offset:49216
	ds_read_b128 v[222:225], v169 offset:62016
	v_exp_f32_e32 v149, v149
	v_exp_f32_e32 v232, v147
	v_cvt_pk_bf16_f32 v155, v199, v201
	v_cvt_pk_bf16_f32 v147, v229, v230
	s_waitcnt lgkmcnt(1)
	v_mfma_f32_32x32x16_bf16 v[80:95], v[180:183], v[132:135], v[80:95]
	s_waitcnt lgkmcnt(0)
	v_mfma_f32_32x32x16_bf16 v[64:79], v[222:225], v[132:135], v[64:79]
	ds_read_b128 v[180:183], v169 offset:49248
	ds_read_b128 v[222:225], v169 offset:62048
	s_waitcnt lgkmcnt(1)
	v_mfma_f32_32x32x16_bf16 v[80:95], v[180:183], v[128:131], v[80:95]
	s_waitcnt lgkmcnt(0)
	v_mfma_f32_32x32x16_bf16 v[64:79], v[222:225], v[128:131], v[64:79]
	ds_read_b128 v[180:183], v169 offset:49280
	ds_read_b128 v[222:225], v169 offset:62080
	s_waitcnt lgkmcnt(1)
	v_mfma_f32_32x32x16_bf16 v[80:95], v[180:183], v[124:127], v[80:95]
	s_waitcnt lgkmcnt(0)
	v_mfma_f32_32x32x16_bf16 v[64:79], v[222:225], v[124:127], v[64:79]
	ds_read_b128 v[180:183], v169 offset:49312
	ds_read_b128 v[222:225], v169 offset:62112
	s_waitcnt lgkmcnt(1)
	v_mfma_f32_32x32x16_bf16 v[80:95], v[180:183], v[120:123], v[80:95]
	s_waitcnt lgkmcnt(0)
	v_mfma_f32_32x32x16_bf16 v[64:79], v[222:225], v[120:123], v[64:79]
	ds_read_b128 v[180:183], v169 offset:49344
	ds_read_b128 v[222:225], v169 offset:62144
	s_waitcnt lgkmcnt(1)
	v_mfma_f32_32x32x16_bf16 v[80:95], v[180:183], v[116:119], v[80:95]
	s_waitcnt lgkmcnt(0)
	v_mfma_f32_32x32x16_bf16 v[64:79], v[222:225], v[116:119], v[64:79]
	ds_read_b128 v[180:183], v169 offset:49376
	ds_read_b128 v[222:225], v169 offset:62176
	s_waitcnt lgkmcnt(1)
	v_mfma_f32_32x32x16_bf16 v[80:95], v[180:183], v[112:115], v[80:95]
	s_waitcnt lgkmcnt(0)
	v_mfma_f32_32x32x16_bf16 v[64:79], v[222:225], v[112:115], v[64:79]
	ds_read_b128 v[180:183], v169 offset:49408
	ds_read_b128 v[222:225], v169 offset:62208
	s_waitcnt lgkmcnt(1)
	v_mfma_f32_32x32x16_bf16 v[80:95], v[180:183], v[108:111], v[80:95]
	s_waitcnt lgkmcnt(0)
	v_mfma_f32_32x32x16_bf16 v[64:79], v[222:225], v[108:111], v[64:79]
	ds_read_b128 v[180:183], v169 offset:49440
	ds_read_b128 v[222:225], v169 offset:62240
	s_waitcnt lgkmcnt(1)
	v_mfma_f32_32x32x16_bf16 v[80:95], v[180:183], v[104:107], v[80:95]
	s_waitcnt lgkmcnt(0)
	v_mfma_f32_32x32x16_bf16 v[64:79], v[222:225], v[104:107], v[64:79]
	ds_read_b128 v[180:183], v169 offset:49472
	ds_read_b128 v[222:225], v169 offset:62272
	s_waitcnt lgkmcnt(1)
	v_mfma_f32_32x32x16_bf16 v[80:95], v[180:183], v[100:103], v[80:95]
	s_waitcnt lgkmcnt(0)
	v_mfma_f32_32x32x16_bf16 v[64:79], v[222:225], v[100:103], v[64:79]
	ds_read_b128 v[180:183], v169 offset:49504
	ds_read_b128 v[222:225], v169 offset:62304
	v_exp_f32_e32 v169, v160
	v_cvt_pk_bf16_f32 v160, v198, v200
	v_add_f32_e32 v146, v169, v146
	s_waitcnt lgkmcnt(1)
	v_mfma_f32_32x32x16_bf16 v[80:95], v[180:183], v[96:99], v[80:95]
	v_exp_f32_e32 v180, v161
	v_exp_f32_e32 v183, v158
	v_cvt_pk_bf16_f32 v158, v184, v185
	v_cvt_pk_bf16_f32 v161, v214, v217
	v_add_f32_e32 v146, v180, v146
	v_cvt_pk_bf16_f32 v150, v169, v180
	v_add_f32_e32 v146, v183, v146
	s_nop 4
	v_max_f32_e32 v169, v81, v81
	v_max_f32_e32 v180, v80, v80
	s_waitcnt lgkmcnt(0)
; #define SBAR() __builtin_amdgcn_sched_barrier(0)
; template <int D0> __device__ __forceinline__ void pv_one_sm(f32x16& od, int vb, bf16x8 pa0, bf16x8 pa1, bf16x8 pa2, bf16x8 pa3, f32x16& q0, f32x16& q1, const float C, const float mnC) {
;   const s16x4 l0 = tr_read<v_rd_off(D0, 0, 0)>(vb), h0 = tr_read<v_rd_off(D0, 0, 1)>(vb), l1 = tr_read<v_rd_off(D0, 1, 0)>(vb), h1 = tr_read<v_rd_off(D0, 1, 1)>(vb);
;   const s16x4 l2 = tr_read<v_rd_off(D0, 2, 0)>(vb), h2 = tr_read<v_rd_off(D0, 2, 1)>(vb), l3 = tr_read<v_rd_off(D0, 3, 0)>(vb), h3 = tr_read<v_rd_off(D0, 3, 1)>(vb);
;   asm volatile("s_waitcnt lgkmcnt(0)" ::: "memory"); SBAR();
;     ...
;   od = __builtin_amdgcn_mfma_f32_32x32x16_bf16(pa0, PK(l0, h0), od, 0, 0, 0);
;   od = __builtin_amdgcn_mfma_f32_32x32x16_bf16(pa1, PK(l1, h1), od, 0, 0, 0);
;   od = __builtin_amdgcn_mfma_f32_32x32x16_bf16(pa2, PK(l2, h2), od, 0, 0, 0);
;   od = __builtin_amdgcn_mfma_f32_32x32x16_bf16(pa3, PK(l3, h3), od, 0, 0, 0);
;     ...
;   if (D0 < 2) {
; #pragma unroll
;     for (int r = 8 * D0; r < 8 * D0 + 8; ++r) q0[r] = __builtin_amdgcn_exp2f(fmaf(q0[r], C, mnC));
;   } else {
; #pragma unroll
;     for (int r = 8 * (D0 - 2); r < 8 * (D0 - 2) + 8; ++r) q1[r] = fmaf(q1[r], C, mnC);
;   }
; }
; __device__ __forceinline__ void pv_sm(f32x16* o, int vb, bf16x8 pa0, bf16x8 pa1, bf16x8 pa2, bf16x8 pa3, f32x16& q0, f32x16& q1, const float C, const float mn) {
;   const float mnC = -mn * C;
;   pv_one_sm<0>(o[0], vb, pa0, pa1, pa2, pa3, q0, q1, C, mnC); pv_one_sm<1>(o[1], vb, pa0, pa1, pa2, pa3, q0, q1, C, mnC);
;   pv_one_sm<2>(o[2], vb, pa0, pa1, pa2, pa3, q0, q1, C, mnC); pv_one_sm<3>(o[3], vb, pa0, pa1, pa2, pa3, q0, q1, C, mnC);
; }
	v_mfma_f32_32x32x16_bf16 v[64:79], v[222:225], v[96:99], v[64:79]
	v_max_f32_e32 v169, v180, v169
	v_max3_f32 v169, v169, v82, v83
	v_max3_f32 v169, v169, v84, v85
	v_max3_f32 v169, v169, v86, v87
	v_max3_f32 v169, v169, v88, v89
	v_max3_f32 v169, v169, v90, v91
	v_exp_f32_e32 v222, v159
	v_max3_f32 v169, v169, v92, v93
	v_exp_f32_e32 v223, v156
	v_max3_f32 v169, v169, v94, v95
	v_exp_f32_e32 v224, v157
	s_nop 0
	v_max3_f32 v169, v169, v64, v65
	v_exp_f32_e32 v225, v154
	v_max3_f32 v169, v169, v66, v67
	v_add_f32_e32 v146, v222, v146
	v_max3_f32 v169, v169, v68, v69
	v_add_f32_e32 v146, v223, v146
	v_max3_f32 v169, v169, v70, v71
	v_add_f32_e32 v146, v224, v146
	v_max3_f32 v169, v169, v72, v73
	v_add_f32_e32 v146, v225, v146
	v_max3_f32 v169, v169, v74, v75
	v_add_f32_e32 v146, v226, v146
	v_max3_f32 v169, v169, v76, v77
	v_add_f32_e32 v146, v227, v146
	v_max3_f32 v169, v169, v78, v79
	v_add_f32_e32 v146, v228, v146
	v_mov_b32_e32 v180, v169
	v_add_f32_e32 v146, v229, v146
	s_nop 0
	v_permlane32_swap_b32_e32 v169, v180
	v_add_f32_e32 v146, v230, v146
	v_max_f32_e32 v180, v180, v180
	v_max_f32_e32 v169, v169, v169
	v_add_f32_e32 v146, v148, v146
	v_max_f32_e32 v169, v169, v180
	v_add_f32_e32 v146, v149, v146
	v_sub_f32_e32 v180, v169, v178
	v_add_f32_e32 v146, v231, v146
	v_cmp_ge_f32_e32 vcc, s56, v180
	v_max_f32_e32 v180, v178, v178
	v_add_f32_e32 v181, v232, v146
	v_max_f32_e32 v180, v180, v169
	v_mov_b32_e32 v182, v181
	s_cmp_eq_u64 vcc, exec
	v_sub_f32_e32 v169, v178, v180
	v_permlane32_swap_b32_e32 v181, v182
	s_cselect_b64 s[8:9], -1, 0
	v_mul_f32_e32 v169, 0x3dd53b94, v169
	v_cvt_pk_bf16_f32 v159, v189, v191
	v_cvt_pk_bf16_f32 v154, v215, v218
	v_cvt_pk_bf16_f32 v156, v216, v219
	v_cvt_pk_bf16_f32 v157, v220, v221
	v_cvt_pk_bf16_f32 v151, v183, v222
	v_cvt_pk_bf16_f32 v152, v223, v224
	v_cvt_pk_bf16_f32 v153, v225, v226
	v_cvt_pk_bf16_f32 v146, v227, v228
	v_cvt_pk_bf16_f32 v148, v148, v149
	v_cvt_pk_bf16_f32 v149, v231, v232
	s_add_i32 s10, s13, 0xfffe8000
	s_mov_b32 s38, s30
	s_mov_b32 s39, s31
	s_add_i32 s11, s13, 0xffff0000
	buffer_load_dwordx4 v[198:201], v170, s[28:31], s10 offen
	buffer_load_dwordx4 v[214:217], v170, s[28:31], s11 offen
	buffer_load_dwordx4 v[218:221], v171, s[36:39], s12 offen
	buffer_load_dwordx4 v[222:225], v176, s[36:39], s12 offen
	buffer_load_dwordx4 v[226:229], v177, s[36:39], s12 offen
	v_exp_f32_e32 v183, v169
	s_lshl_b32 s16, s44, 14
	v_add_u32_e32 v169, s16, v168
	ds_read_b64_tr_b16 v[230:231], v169 offset:0
	ds_read_b64_tr_b16 v[232:233], v169 offset:0x800
	ds_read_b64_tr_b16 v[234:235], v169 offset:0x1000
	ds_read_b64_tr_b16 v[236:237], v169 offset:0x1800
	ds_read_b64_tr_b16 v[238:239], v169 offset:0x2000
	ds_read_b64_tr_b16 v[240:241], v169 offset:0x2800
	ds_read_b64_tr_b16 v[242:243], v169 offset:0x3000
	ds_read_b64_tr_b16 v[244:245], v169 offset:0x3800
	s_waitcnt lgkmcnt(0)
	s_nop 0
	v_mfma_f32_32x32x16_bf16 v[0:15], v[158:161], v[230:233], v[0:15]
	ds_read_b64_tr_b16 v[230:231], v169 offset:0x200
	ds_read_b64_tr_b16 v[232:233], v169 offset:0xa00
	v_mfma_f32_32x32x16_bf16 v[0:15], v[154:157], v[234:237], v[0:15]
	ds_read_b64_tr_b16 v[234:235], v169 offset:0x1200
	ds_read_b64_tr_b16 v[236:237], v169 offset:0x1a00
	v_mfma_f32_32x32x16_bf16 v[0:15], v[150:153], v[238:241], v[0:15]
	ds_read_b64_tr_b16 v[238:239], v169 offset:0x2200
	ds_read_b64_tr_b16 v[240:241], v169 offset:0x2a00
	v_mfma_f32_32x32x16_bf16 v[0:15], v[146:149], v[242:245], v[0:15]
	ds_read_b64_tr_b16 v[242:243], v169 offset:0x3200
	ds_read_b64_tr_b16 v[244:245], v169 offset:0x3a00
	s_waitcnt lgkmcnt(0)
	v_mfma_f32_32x32x16_bf16 v[48:63], v[158:161], v[230:233], v[48:63]
	ds_read_b64_tr_b16 v[230:231], v169 offset:0x400
	ds_read_b64_tr_b16 v[232:233], v169 offset:0xc00
	v_mfma_f32_32x32x16_bf16 v[48:63], v[154:157], v[234:237], v[48:63]
	ds_read_b64_tr_b16 v[234:235], v169 offset:0x1400
	ds_read_b64_tr_b16 v[236:237], v169 offset:0x1c00
	v_mfma_f32_32x32x16_bf16 v[48:63], v[150:153], v[238:241], v[48:63]
	ds_read_b64_tr_b16 v[238:239], v169 offset:0x2400
	ds_read_b64_tr_b16 v[240:241], v169 offset:0x2c00
	v_mfma_f32_32x32x16_bf16 v[48:63], v[146:149], v[242:245], v[48:63]
	ds_read_b64_tr_b16 v[242:243], v169 offset:0x3400
	ds_read_b64_tr_b16 v[244:245], v169 offset:0x3c00
	s_waitcnt lgkmcnt(0)
	v_mfma_f32_32x32x16_bf16 v[32:47], v[158:161], v[230:233], v[32:47]
	ds_read_b64_tr_b16 v[230:231], v169 offset:0x600
	ds_read_b64_tr_b16 v[232:233], v169 offset:0xe00
	v_mfma_f32_32x32x16_bf16 v[32:47], v[154:157], v[234:237], v[32:47]
	ds_read_b64_tr_b16 v[234:235], v169 offset:0x1600
	ds_read_b64_tr_b16 v[236:237], v169 offset:0x1e00
	v_mfma_f32_32x32x16_bf16 v[32:47], v[150:153], v[238:241], v[32:47]
	ds_read_b64_tr_b16 v[238:239], v169 offset:0x2600
	ds_read_b64_tr_b16 v[240:241], v169 offset:0x2e00
	v_mfma_f32_32x32x16_bf16 v[32:47], v[146:149], v[242:245], v[32:47]
	ds_read_b64_tr_b16 v[242:243], v169 offset:0x3600
	ds_read_b64_tr_b16 v[244:245], v169 offset:0x3e00
	s_waitcnt lgkmcnt(0)
	v_mfma_f32_32x32x16_bf16 v[16:31], v[158:161], v[230:233], v[16:31]
	s_waitcnt vmcnt(0)
	s_lshl_b32 s15, s51, 14
	s_mul_i32 s17, s51, 0x6400
	v_cndmask_b32_e64 v183, v183, 1.0, s[8:9]
	v_cmp_gt_f32_e32 vcc, 1.0, v183
	v_mfma_f32_32x32x16_bf16 v[16:31], v[154:157], v[234:237], v[16:31]
	v_add_u32_e32 v154, s15, v175
	s_waitcnt vmcnt(4)
	ds_write_b128 v154, v[198:201]
	s_waitcnt vmcnt(3)
	ds_write_b128 v154, v[214:217] offset:8192
	v_mfma_f32_32x32x16_bf16 v[16:31], v[150:153], v[238:241], v[16:31]
	v_add_u32_e32 v150, s17, v173
	s_waitcnt vmcnt(2)
	ds_write_b128 v150, v[218:221] offset:49152
	s_waitcnt vmcnt(1)
	ds_write_b128 v150, v[222:225] offset:49280
	s_waitcnt vmcnt(0)
	ds_write_b128 v150, v[226:229] offset:49408
	v_mfma_f32_32x32x16_bf16 v[16:31], v[146:149], v[242:245], v[16:31]
	s_cbranch_vccz .LBB0_2543
	s_and_saveexec_b64 s[10:11], s[6:7]
	ds_write_b32 v166, v183 offset:128
	s_or_b64 exec, exec, s[10:11]
	s_waitcnt lgkmcnt(0)
	v_add_u32_e32 v158, v165, v162
	ds_read_b128 v[146:149], v158 offset:224
	ds_read_b128 v[150:153], v158 offset:192
	ds_read_b128 v[154:157], v158 offset:160
	ds_read_b128 v[158:161], v158 offset:128
	s_waitcnt lgkmcnt(3)
	v_pk_mul_f32 v[12:13], v[12:13], v[146:147]
	s_waitcnt lgkmcnt(2)
	v_pk_mul_f32 v[8:9], v[8:9], v[150:151]
	s_waitcnt lgkmcnt(1)
	v_pk_mul_f32 v[4:5], v[4:5], v[154:155]
	v_pk_mul_f32 v[14:15], v[14:15], v[148:149]
	v_pk_mul_f32 v[10:11], v[10:11], v[152:153]
	v_pk_mul_f32 v[6:7], v[6:7], v[156:157]
	s_waitcnt lgkmcnt(0)
	v_pk_mul_f32 v[2:3], v[2:3], v[160:161]
	v_pk_mul_f32 v[0:1], v[0:1], v[158:159]
	v_pk_mul_f32 v[60:61], v[60:61], v[146:147]
	v_pk_mul_f32 v[56:57], v[56:57], v[150:151]
	v_pk_mul_f32 v[52:53], v[52:53], v[154:155]
	v_pk_mul_f32 v[62:63], v[62:63], v[148:149]
	v_pk_mul_f32 v[58:59], v[58:59], v[152:153]
	v_pk_mul_f32 v[54:55], v[54:55], v[156:157]
	v_pk_mul_f32 v[50:51], v[50:51], v[160:161]
	v_pk_mul_f32 v[48:49], v[48:49], v[158:159]
	v_pk_mul_f32 v[44:45], v[44:45], v[146:147]
	v_pk_mul_f32 v[40:41], v[40:41], v[150:151]
	v_pk_mul_f32 v[36:37], v[36:37], v[154:155]
	v_pk_mul_f32 v[46:47], v[46:47], v[148:149]
	v_pk_mul_f32 v[42:43], v[42:43], v[152:153]
	v_pk_mul_f32 v[38:39], v[38:39], v[156:157]
	v_pk_mul_f32 v[34:35], v[34:35], v[160:161]
	v_pk_mul_f32 v[32:33], v[32:33], v[158:159]
	v_pk_mul_f32 v[28:29], v[28:29], v[146:147]
	v_pk_mul_f32 v[24:25], v[24:25], v[150:151]
	v_pk_mul_f32 v[20:21], v[20:21], v[154:155]
	v_pk_mul_f32 v[30:31], v[30:31], v[148:149]
	v_pk_mul_f32 v[26:27], v[26:27], v[152:153]
	v_pk_mul_f32 v[22:23], v[22:23], v[156:157]
	v_pk_mul_f32 v[18:19], v[18:19], v[160:161]
	v_pk_mul_f32 v[16:17], v[16:17], v[158:159]

; #define SBAR() __builtin_amdgcn_sched_barrier(0)
; #define SWRITE(b, i) do { STG_T() const int _sv = VSTV(), _sk = LDSK(); *(u32x4*)(V_lds + (b) * SHM_V + _sv) = sr_[i].vs0; *(u32x4*)(V_lds + (b) * SHM_V + _sv + 8192) = sr_[i].vs1; \
;     _Pragma("unroll") for (int _p = 0; _p < NP; ++_p) *(u32x4*)(K_lds + (b) * KT + _sk + _p * 128) = sr_[i].ks[_p]; } while (0)
; #define SWAIT() do { if constexpr (SD == 2) { if constexpr (NP == 1) asm volatile("s_waitcnt vmcnt(3)" ::: "memory"); else asm volatile("s_waitcnt vmcnt(5)" ::: "memory"); } else asm volatile("s_waitcnt vmcnt(0)" ::: "memory"); } while (0)
; #define RESC(a) do { if (__any((a) < 1.f)) { if (hi == 0) al_l[r32] = (a); asm volatile("s_waitcnt lgkmcnt(0)" ::: "memory"); \
;     _Pragma("unroll") for (int d = 0; d < 4; ++d) _Pragma("unroll") for (int r = 0; r < 16; ++r) o[d][r] *= al_l[crow(r, hi)]; } } while (0)
; #define QKT(P0, P1, KS) do { if constexpr (MI) qkt_mi<NQK>(P0, P1, KS, qr, r32, hi, minit); else qkt<NQK>(P0, P1, KS, qr, r32, hi); } while (0)
; #define DECIDE(P0, P1, MN, AL) do { if constexpr (MI) decide_mi(P0, P1, minit, Mref, AL, thr2, false); else decideSM(P0, P1, m_reg, MN, AL, C, thr); } while (0)
; #define PVSM(VB, P0, P1, MN) do { if constexpr (MI) pv_mi(o, VB, pa0, pa1, pa2, pa3, P0); else pv_sm(o, VB, pa0, pa1, pa2, pa3, P0, P1, C, MN); } while (0)
; #define ROT() do { const int _r = rp; rp = rc; rc = rn; rn = _r; } while (0)
; template <int NQK, int SD, bool MI> ...
;     ...
;   for (int j = 1; j + 1 < NT; j += 2) {
;     SBAR(); QKT(pB0, pB1, K_lds + rc * KT);
;     finishSM(pA0, pA1, alA, l_reg, pa0, pa1, pa2, pa3); DECIDE(pB0, pB1, mnB, alB); SBAR();
;     SLOAD(SO, (j + SD) * 64); SBAR();
;     PVSM(vb0 + rp * SHM_V, pB0, pB1, mnB);
;     SWAIT(); SWRITE(rn, SE);
;     RESC(alB); __syncthreads(); ROT();
;     SBAR(); QKT(pA0, pA1, K_lds + rc * KT);
;     finishSM(pB0, pB1, alB, l_reg, pa0, pa1, pa2, pa3); DECIDE(pA0, pA1, mnA, alA); SBAR();
;     if (SD == 1 || j + 3 < NT) SLOAD(SE, (j + 1 + SD) * 64); SBAR();
;     PVSM(vb0 + rp * SHM_V, pA0, pA1, mnA);
;     SWAIT(); SWRITE(rn, SO);
;     RESC(alA); __syncthreads(); ROT();
;   }
;   SBAR(); QKT(pB0, pB1, K_lds + rc * KT);
;   finishSM(pA0, pA1, alA, l_reg, pa0, pa1, pa2, pa3); DECIDE(pB0, pB1, mnB, alB); SBAR();
;   PVSM(vb0 + rp * SHM_V, pB0, pB1, mnB);
;   RESC(alB);
;   finishSM(pB0, pB1, alB, l_reg, pa0, pa1, pa2, pa3); SBAR();
.LBB0_2547:
	v_cndmask_b32_e64 v178, v189, v178, s[8:9]
	v_mul_f32_e32 v146, 0xbdd53b94, v178
	v_add_f32_e32 v181, v181, v182
	v_fmamk_f32 v80, v80, 0x3dd53b94, v146
	v_fmac_f32_e32 v181, v179, v167
	v_add_f32_e32 v167, v184, v185
	v_exp_f32_e32 v184, v80
	v_fmamk_f32 v80, v81, 0x3dd53b94, v146
	v_exp_f32_e32 v185, v80
	v_fmamk_f32 v80, v82, 0x3dd53b94, v146
	v_exp_f32_e32 v189, v80
	v_fmamk_f32 v80, v83, 0x3dd53b94, v146
	v_exp_f32_e32 v191, v80
	v_fmamk_f32 v80, v84, 0x3dd53b94, v146
	v_exp_f32_e32 v198, v80
	v_fmamk_f32 v80, v85, 0x3dd53b94, v146
	v_exp_f32_e32 v200, v80
	v_fmamk_f32 v80, v86, 0x3dd53b94, v146
	v_exp_f32_e32 v214, v80
	v_fmamk_f32 v80, v87, 0x3dd53b94, v146
	v_exp_f32_e32 v217, v80
	v_fmamk_f32 v80, v88, 0x3dd53b94, v146
	v_exp_f32_e32 v215, v80
	v_fmamk_f32 v80, v89, 0x3dd53b94, v146
	v_exp_f32_e32 v218, v80
	v_fmamk_f32 v80, v90, 0x3dd53b94, v146
	v_exp_f32_e32 v199, v80
	v_fmamk_f32 v80, v91, 0x3dd53b94, v146
	v_exp_f32_e32 v201, v80
	v_fmamk_f32 v80, v92, 0x3dd53b94, v146
	v_exp_f32_e32 v216, v80
	v_fmamk_f32 v80, v93, 0x3dd53b94, v146
	v_exp_f32_e32 v219, v80
	v_fmamk_f32 v80, v94, 0x3dd53b94, v146
	v_exp_f32_e32 v220, v80
	v_fmamk_f32 v80, v95, 0x3dd53b94, v146
	v_exp_f32_e32 v221, v80
	s_add_i32 s12, s12, 0x30000
	s_add_i32 s13, s13, 0x20000
	s_add_i32 s45, s45, 2
	v_pk_fma_f32 v[160:161], v[64:65], s[92:93], v[146:147] op_sel_hi:[1,0,0]
	v_pk_fma_f32 v[158:159], v[66:67], s[92:93], v[146:147] op_sel_hi:[1,0,0]
	v_pk_fma_f32 v[156:157], v[68:69], s[92:93], v[146:147] op_sel_hi:[1,0,0]
	v_pk_fma_f32 v[154:155], v[70:71], s[92:93], v[146:147] op_sel_hi:[1,0,0]
	v_pk_fma_f32 v[152:153], v[72:73], s[92:93], v[146:147] op_sel_hi:[1,0,0]
	v_pk_fma_f32 v[150:151], v[74:75], s[92:93], v[146:147] op_sel_hi:[1,0,0]
	v_pk_fma_f32 v[148:149], v[76:77], s[92:93], v[146:147] op_sel_hi:[1,0,0]
	v_pk_fma_f32 v[146:147], v[78:79], s[92:93], v[146:147] op_sel_hi:[1,0,0]
	v_fmac_f32_e32 v167, v181, v183
	s_cmpk_gt_u32 s45, 0x100
	s_waitcnt lgkmcnt(0)
	s_cbranch_scc1 .Lmla_exitbar
	s_mov_b32 s8, s51
	s_mov_b32 s51, s14
	v_mov_b32_e32 v179, v180
	s_mov_b32 s14, s44
	s_mov_b32 s44, s8
	s_mul_i32 s8, s14, 0x6400
	v_add_u32_e32 v169, s8, v174
	s_branch .LBB0_2539
.Lmla_exitbar:
	s_barrier
.LBB0_2549:
	s_add_i32 s8, s16, 16
	v_add3_u32 v174, s8, v172, v162
	ds_read_b128 v[64:67], v174 offset:61952
	ds_read_b128 v[68:71], v174 offset:49152
	ds_read_b128 v[170:173], v174 offset:49184
	s_waitcnt lgkmcnt(1)
	v_mfma_f32_32x32x16_bf16 v[80:95], v[68:71], v[140:143], 0
	v_mfma_f32_32x32x16_bf16 v[64:79], v[64:67], v[140:143], 0
	ds_read_b128 v[140:143], v174 offset:61984
	s_waitcnt lgkmcnt(1)
	v_mfma_f32_32x32x16_bf16 v[80:95], v[170:173], v[136:139], v[80:95]
	s_waitcnt lgkmcnt(0)
	v_mfma_f32_32x32x16_bf16 v[64:79], v[140:143], v[136:139], v[64:79]
	ds_read_b128 v[136:139], v174 offset:49216
	ds_read_b128 v[140:143], v174 offset:62016
	s_waitcnt lgkmcnt(1)
	v_mfma_f32_32x32x16_bf16 v[80:95], v[136:139], v[132:135], v[80:95]
	s_waitcnt lgkmcnt(0)
	v_mfma_f32_32x32x16_bf16 v[64:79], v[140:143], v[132:135], v[64:79]
	ds_read_b128 v[132:135], v174 offset:49248
	ds_read_b128 v[136:139], v174 offset:62048
	s_waitcnt lgkmcnt(1)
	v_mfma_f32_32x32x16_bf16 v[80:95], v[132:135], v[128:131], v[80:95]
	s_waitcnt lgkmcnt(0)
	v_mfma_f32_32x32x16_bf16 v[64:79], v[136:139], v[128:131], v[64:79]
	ds_read_b128 v[128:131], v174 offset:49280
	ds_read_b128 v[132:135], v174 offset:62080
	s_waitcnt lgkmcnt(1)
	v_mfma_f32_32x32x16_bf16 v[80:95], v[128:131], v[124:127], v[80:95]
	s_waitcnt lgkmcnt(0)
	v_mfma_f32_32x32x16_bf16 v[64:79], v[132:135], v[124:127], v[64:79]
	ds_read_b128 v[124:127], v174 offset:49312
	ds_read_b128 v[128:131], v174 offset:62112
	s_waitcnt lgkmcnt(1)
	v_mfma_f32_32x32x16_bf16 v[80:95], v[124:127], v[120:123], v[80:95]
	s_waitcnt lgkmcnt(0)
	v_mfma_f32_32x32x16_bf16 v[64:79], v[128:131], v[120:123], v[64:79]
	ds_read_b128 v[120:123], v174 offset:49344
	ds_read_b128 v[124:127], v174 offset:62144
	s_waitcnt lgkmcnt(1)
	v_mfma_f32_32x32x16_bf16 v[80:95], v[120:123], v[116:119], v[80:95]
	s_waitcnt lgkmcnt(0)
	v_mfma_f32_32x32x16_bf16 v[64:79], v[124:127], v[116:119], v[64:79]
	ds_read_b128 v[116:119], v174 offset:49376
	ds_read_b128 v[120:123], v174 offset:62176
	s_waitcnt lgkmcnt(1)
	v_mfma_f32_32x32x16_bf16 v[80:95], v[116:119], v[112:115], v[80:95]
	s_waitcnt lgkmcnt(0)
	v_mfma_f32_32x32x16_bf16 v[64:79], v[120:123], v[112:115], v[64:79]
	ds_read_b128 v[112:115], v174 offset:49408
	ds_read_b128 v[116:119], v174 offset:62208
	v_exp_f32_e32 v120, v146
	v_exp_f32_e32 v121, v147
	s_waitcnt lgkmcnt(1)
	v_mfma_f32_32x32x16_bf16 v[80:95], v[112:115], v[108:111], v[80:95]
	s_waitcnt lgkmcnt(0)
	v_mfma_f32_32x32x16_bf16 v[64:79], v[116:119], v[108:111], v[64:79]
	ds_read_b128 v[108:111], v174 offset:49440
	ds_read_b128 v[112:115], v174 offset:62240
	v_exp_f32_e32 v116, v150
	v_exp_f32_e32 v117, v151
	v_exp_f32_e32 v118, v148
	v_exp_f32_e32 v119, v149
	s_waitcnt lgkmcnt(1)
	v_mfma_f32_32x32x16_bf16 v[80:95], v[108:111], v[104:107], v[80:95]
	s_waitcnt lgkmcnt(0)
	v_mfma_f32_32x32x16_bf16 v[64:79], v[112:115], v[104:107], v[64:79]
	ds_read_b128 v[104:107], v174 offset:49472
	ds_read_b128 v[108:111], v174 offset:62272
	v_exp_f32_e32 v114, v152
	v_exp_f32_e32 v115, v153
	s_waitcnt lgkmcnt(1)
	v_mfma_f32_32x32x16_bf16 v[80:95], v[104:107], v[100:103], v[80:95]
	s_waitcnt lgkmcnt(0)
	v_mfma_f32_32x32x16_bf16 v[64:79], v[108:111], v[100:103], v[64:79]
	ds_read_b128 v[100:103], v174 offset:49504
	ds_read_b128 v[104:107], v174 offset:62304
	v_exp_f32_e32 v108, v156
	v_exp_f32_e32 v109, v157
	v_exp_f32_e32 v110, v154
	v_exp_f32_e32 v111, v155
	s_waitcnt lgkmcnt(1)
; #define SBAR() __builtin_amdgcn_sched_barrier(0)
; #define RESC(a) do { if (__any((a) < 1.f)) { if (hi == 0) al_l[r32] = (a); asm volatile("s_waitcnt lgkmcnt(0)" ::: "memory"); \
;     _Pragma("unroll") for (int d = 0; d < 4; ++d) _Pragma("unroll") for (int r = 0; r < 16; ++r) o[d][r] *= al_l[crow(r, hi)]; } } while (0)
; #define QKT(P0, P1, KS) do { if constexpr (MI) qkt_mi<NQK>(P0, P1, KS, qr, r32, hi, minit); else qkt<NQK>(P0, P1, KS, qr, r32, hi); } while (0)
; #define DECIDE(P0, P1, MN, AL) do { if constexpr (MI) decide_mi(P0, P1, minit, Mref, AL, thr2, false); else decideSM(P0, P1, m_reg, MN, AL, C, thr); } while (0)
; #define PVSM(VB, P0, P1, MN) do { if constexpr (MI) pv_mi(o, VB, pa0, pa1, pa2, pa3, P0); else pv_sm(o, VB, pa0, pa1, pa2, pa3, P0, P1, C, MN); } while (0)
; template <int NQK, int SD, bool MI> ...
;     ...
;   SBAR(); QKT(pB0, pB1, K_lds + rc * KT);
;   finishSM(pA0, pA1, alA, l_reg, pa0, pa1, pa2, pa3); DECIDE(pB0, pB1, mnB, alB); SBAR();
;   PVSM(vb0 + rp * SHM_V, pB0, pB1, mnB);
;   RESC(alB);
;   finishSM(pB0, pB1, alB, l_reg, pa0, pa1, pa2, pa3); SBAR();
;   pv_d0(o, vb0 + rc * SHM_V, pa0, pa1, pa2, pa3);
	v_mfma_f32_32x32x16_bf16 v[80:95], v[100:103], v[96:99], v[80:95]
	v_cvt_pk_bf16_f32 v100, v215, v218
	v_cvt_pk_bf16_f32 v101, v199, v201
	v_cvt_pk_bf16_f32 v102, v216, v219
	v_cvt_pk_bf16_f32 v103, v220, v221
	s_waitcnt lgkmcnt(0)
	v_mfma_f32_32x32x16_bf16 v[64:79], v[104:107], v[96:99], v[64:79]
	v_add_f32_e32 v96, 0, v184
	v_add_f32_e32 v96, v185, v96
	v_add_f32_e32 v96, v189, v96
	v_add_f32_e32 v96, v191, v96
	v_add_f32_e32 v96, v198, v96
	v_add_f32_e32 v96, v200, v96
	v_add_f32_e32 v96, v214, v96
	v_add_f32_e32 v96, v217, v96
	v_add_f32_e32 v96, v215, v96
	v_add_f32_e32 v96, v218, v96
	v_add_f32_e32 v96, v199, v96
	v_add_f32_e32 v96, v201, v96
	v_exp_f32_e32 v104, v160
	v_add_f32_e32 v96, v216, v96
	v_exp_f32_e32 v105, v161
	v_add_f32_e32 v96, v219, v96
	v_exp_f32_e32 v106, v158
	v_add_f32_e32 v96, v220, v96
	v_exp_f32_e32 v107, v159
	v_add_f32_e32 v96, v221, v96
	v_add_f32_e32 v96, v104, v96
	v_add_f32_e32 v96, v105, v96
	v_add_f32_e32 v96, v106, v96
	v_add_f32_e32 v96, v107, v96
	v_add_f32_e32 v96, v108, v96
	v_add_f32_e32 v96, v109, v96
	v_add_f32_e32 v96, v110, v96
	v_add_f32_e32 v96, v111, v96
	v_add_f32_e32 v96, v114, v96
	v_add_f32_e32 v96, v115, v96
	v_cvt_pk_bf16_f32 v104, v104, v105
	v_cvt_pk_bf16_f32 v105, v106, v107
	v_cvt_pk_bf16_f32 v106, v108, v109
	v_cvt_pk_bf16_f32 v108, v114, v115
	v_max_f32_e32 v114, v81, v81
	v_max_f32_e32 v115, v80, v80
	v_max_f32_e32 v114, v115, v114
	v_max3_f32 v114, v114, v82, v83
	v_max3_f32 v114, v114, v84, v85
	v_max3_f32 v114, v114, v86, v87
	v_max3_f32 v114, v114, v88, v89
	v_max3_f32 v114, v114, v90, v91
	v_max3_f32 v114, v114, v92, v93
	v_max3_f32 v114, v114, v94, v95
	v_max3_f32 v114, v114, v64, v65
	v_max3_f32 v114, v114, v66, v67
	v_max3_f32 v114, v114, v68, v69
	v_max3_f32 v114, v114, v70, v71
	v_max3_f32 v114, v114, v72, v73
	v_max3_f32 v114, v114, v74, v75
	v_max3_f32 v114, v114, v76, v77
	v_max3_f32 v114, v114, v78, v79
	v_mov_b32_e32 v115, v114
	s_nop 1
	v_permlane32_swap_b32_e32 v114, v115
	v_max_f32_e32 v115, v115, v115
	v_max_f32_e32 v114, v114, v114
	v_max_f32_e32 v114, v114, v115
	v_sub_f32_e32 v115, v114, v178
	v_cmp_ge_f32_e32 vcc, s56, v115
	v_max_f32_e32 v115, v178, v178
	v_add_f32_e32 v96, v116, v96
	v_max_f32_e32 v115, v115, v114
	v_add_f32_e32 v96, v117, v96
	v_sub_f32_e32 v114, v178, v115
	v_add_f32_e32 v96, v118, v96
	v_mul_f32_e32 v114, 0x3dd53b94, v114
	v_add_f32_e32 v96, v119, v96
	v_exp_f32_e32 v114, v114
	v_add_f32_e32 v96, v120, v96
	v_add_f32_e32 v112, v121, v96
	s_cmp_eq_u64 vcc, exec
	v_mov_b32_e32 v113, v112
	s_cselect_b64 s[8:9], -1, 0
	s_nop 0
	v_permlane32_swap_b32_e32 v112, v113
	v_cndmask_b32_e64 v114, v114, 1.0, s[8:9]
	v_cvt_pk_bf16_f32 v96, v184, v185
	v_cvt_pk_bf16_f32 v97, v189, v191
	v_cvt_pk_bf16_f32 v98, v198, v200
	v_cvt_pk_bf16_f32 v99, v214, v217
	v_cvt_pk_bf16_f32 v107, v110, v111
	v_cvt_pk_bf16_f32 v109, v116, v117
	v_cvt_pk_bf16_f32 v110, v118, v119
	v_cvt_pk_bf16_f32 v111, v120, v121
	v_add_u32_e32 v132, s15, v168
	ds_read_b64_tr_b16 v[116:117], v132 offset:0
	ds_read_b64_tr_b16 v[118:119], v132 offset:0x800
	ds_read_b64_tr_b16 v[120:121], v132 offset:0x1000
	ds_read_b64_tr_b16 v[122:123], v132 offset:0x1800
	ds_read_b64_tr_b16 v[124:125], v132 offset:0x2000
	ds_read_b64_tr_b16 v[126:127], v132 offset:0x2800
	ds_read_b64_tr_b16 v[128:129], v132 offset:0x3000
	ds_read_b64_tr_b16 v[130:131], v132 offset:0x3800
	s_waitcnt lgkmcnt(0)
	s_nop 0
	v_mfma_f32_32x32x16_bf16 v[0:15], v[96:99], v[116:119], v[0:15]
	ds_read_b64_tr_b16 v[116:117], v132 offset:0x200
	ds_read_b64_tr_b16 v[118:119], v132 offset:0xa00
	v_mfma_f32_32x32x16_bf16 v[0:15], v[100:103], v[120:123], v[0:15]
	ds_read_b64_tr_b16 v[120:121], v132 offset:0x1200
	ds_read_b64_tr_b16 v[122:123], v132 offset:0x1a00
	v_mfma_f32_32x32x16_bf16 v[0:15], v[104:107], v[124:127], v[0:15]
	ds_read_b64_tr_b16 v[124:125], v132 offset:0x2200
	ds_read_b64_tr_b16 v[126:127], v132 offset:0x2a00
	v_mfma_f32_32x32x16_bf16 v[0:15], v[108:111], v[128:131], v[0:15]
	ds_read_b64_tr_b16 v[128:129], v132 offset:0x3200
	ds_read_b64_tr_b16 v[130:131], v132 offset:0x3a00
	s_waitcnt lgkmcnt(0)
	v_mfma_f32_32x32x16_bf16 v[48:63], v[96:99], v[116:119], v[48:63]
	ds_read_b64_tr_b16 v[116:117], v132 offset:0x400
	ds_read_b64_tr_b16 v[118:119], v132 offset:0xc00
	v_mfma_f32_32x32x16_bf16 v[48:63], v[100:103], v[120:123], v[48:63]
	ds_read_b64_tr_b16 v[120:121], v132 offset:0x1400
	ds_read_b64_tr_b16 v[122:123], v132 offset:0x1c00
	v_mfma_f32_32x32x16_bf16 v[48:63], v[104:107], v[124:127], v[48:63]
	ds_read_b64_tr_b16 v[124:125], v132 offset:0x2400
	ds_read_b64_tr_b16 v[126:127], v132 offset:0x2c00
	v_mfma_f32_32x32x16_bf16 v[48:63], v[108:111], v[128:131], v[48:63]
	ds_read_b64_tr_b16 v[128:129], v132 offset:0x3400
	ds_read_b64_tr_b16 v[130:131], v132 offset:0x3c00
	s_waitcnt lgkmcnt(0)
	v_mfma_f32_32x32x16_bf16 v[32:47], v[96:99], v[116:119], v[32:47]
	ds_read_b64_tr_b16 v[116:117], v132 offset:0x600
	ds_read_b64_tr_b16 v[118:119], v132 offset:0xe00
	v_mfma_f32_32x32x16_bf16 v[32:47], v[100:103], v[120:123], v[32:47]
	ds_read_b64_tr_b16 v[120:121], v132 offset:0x1600
	ds_read_b64_tr_b16 v[122:123], v132 offset:0x1e00
	v_mfma_f32_32x32x16_bf16 v[32:47], v[104:107], v[124:127], v[32:47]
	ds_read_b64_tr_b16 v[124:125], v132 offset:0x2600
	ds_read_b64_tr_b16 v[126:127], v132 offset:0x2e00
	v_mfma_f32_32x32x16_bf16 v[32:47], v[108:111], v[128:131], v[32:47]
	ds_read_b64_tr_b16 v[128:129], v132 offset:0x3600
	ds_read_b64_tr_b16 v[130:131], v132 offset:0x3e00
	s_waitcnt lgkmcnt(0)
	v_mfma_f32_32x32x16_bf16 v[16:31], v[96:99], v[116:119], v[16:31]
	v_cmp_gt_f32_e32 vcc, 1.0, v114
	v_mfma_f32_32x32x16_bf16 v[16:31], v[100:103], v[120:123], v[16:31]
	v_mfma_f32_32x32x16_bf16 v[16:31], v[104:107], v[124:127], v[16:31]
	v_mfma_f32_32x32x16_bf16 v[16:31], v[108:111], v[128:131], v[16:31]
	s_cbranch_vccz .LBB0_2553
	s_and_saveexec_b64 s[10:11], s[6:7]
	s_movk_i32 s51, 0x4000
	v_readlane_b32 s44, v255, 32
	v_readlane_b32 s45, v255, 33
	ds_write_b32 v166, v114 offset:128
	s_or_b64 exec, exec, s[10:11]
	s_waitcnt lgkmcnt(0)
	v_add_u32_e32 v108, v165, v162
	ds_read_b128 v[96:99], v108 offset:224
	ds_read_b128 v[100:103], v108 offset:192
	ds_read_b128 v[104:107], v108 offset:160
	ds_read_b128 v[108:111], v108 offset:128
	s_waitcnt lgkmcnt(3)
	v_pk_mul_f32 v[12:13], v[12:13], v[96:97]
	s_waitcnt lgkmcnt(2)
	v_pk_mul_f32 v[8:9], v[8:9], v[100:101]
	s_waitcnt lgkmcnt(1)
	v_pk_mul_f32 v[4:5], v[4:5], v[104:105]
	v_pk_mul_f32 v[14:15], v[14:15], v[98:99]
	v_pk_mul_f32 v[10:11], v[10:11], v[102:103]
	v_pk_mul_f32 v[6:7], v[6:7], v[106:107]
	s_waitcnt lgkmcnt(0)
	v_pk_mul_f32 v[2:3], v[2:3], v[110:111]
	v_pk_mul_f32 v[0:1], v[0:1], v[108:109]
	v_pk_mul_f32 v[60:61], v[60:61], v[96:97]
	v_pk_mul_f32 v[56:57], v[56:57], v[100:101]
	v_pk_mul_f32 v[52:53], v[52:53], v[104:105]
	v_pk_mul_f32 v[62:63], v[62:63], v[98:99]
	v_pk_mul_f32 v[58:59], v[58:59], v[102:103]
	v_pk_mul_f32 v[54:55], v[54:55], v[106:107]
	v_pk_mul_f32 v[50:51], v[50:51], v[110:111]
	v_pk_mul_f32 v[48:49], v[48:49], v[108:109]
	v_pk_mul_f32 v[44:45], v[44:45], v[96:97]
	v_pk_mul_f32 v[40:41], v[40:41], v[100:101]
	v_pk_mul_f32 v[36:37], v[36:37], v[104:105]
	v_pk_mul_f32 v[46:47], v[46:47], v[98:99]
	v_pk_mul_f32 v[42:43], v[42:43], v[102:103]
	v_pk_mul_f32 v[38:39], v[38:39], v[106:107]
	v_pk_mul_f32 v[34:35], v[34:35], v[110:111]
	v_pk_mul_f32 v[32:33], v[32:33], v[108:109]
	v_pk_mul_f32 v[28:29], v[28:29], v[96:97]
	v_pk_mul_f32 v[24:25], v[24:25], v[100:101]
	v_pk_mul_f32 v[20:21], v[20:21], v[104:105]
	v_pk_mul_f32 v[30:31], v[30:31], v[98:99]
	v_pk_mul_f32 v[26:27], v[26:27], v[102:103]
	v_pk_mul_f32 v[22:23], v[22:23], v[106:107]
	v_pk_mul_f32 v[18:19], v[18:19], v[110:111]
	v_pk_mul_f32 v[16:17], v[16:17], v[108:109]
	s_branch .LBB0_2554
